# attention loops modes 0/2: remaining induction-pointer tile loads (step 1 K/V, step 4 K, step 5 V) also in SADDR form; 8 more VALU removed per 8 steps
# speedup vs baseline: 1.0039x; 1.0039x over previous
.LBB0_641:
	s_add_i32 s24, s23, -7
	s_lshl_b32 s92, s24, 13
	s_add_u32 vcc_lo, s100, s92
	s_addc_u32 vcc_hi, s101, 0
	global_load_dwordx4 v[52:55], v248, vcc
	s_add_i32 s24, s23, -8
	s_lshl_b32 s92, s24, 7
	s_add_u32 vcc_lo, s98, s92
	s_addc_u32 vcc_hi, s99, 0
	global_load_dwordx4 v[56:59], v249, vcc
	s_mul_i32 s26, s25, 0x2400
	s_add_i32 s24, s23, -7
	s_add_i32 s27, s26, 0xffffdc00
	s_cmp_lg_u32 s25, 0
	s_cselect_b32 s27, s27, 0x9000
	v_add_u32_e32 v1, s27, v163
	ds_read_b128 v[60:63], v1 offset:36864
	ds_read_b128 v[114:117], v1 offset:36896
	ds_read_b128 v[118:121], v1 offset:41472
	ds_read_b128 v[134:137], v1 offset:41504
	ds_read_b128 v[146:149], v1 offset:36928
	ds_read_b128 v[150:153], v1 offset:36960
	ds_read_b128 v[196:199], v1 offset:41536
	ds_read_b128 v[200:203], v1 offset:41568
	s_setprio 3
	v_cvt_pk_bf16_f32 v204, v102, v103
	v_cvt_pk_bf16_f32 v205, v104, v105
	v_cvt_pk_bf16_f32 v206, v98, v99
	v_cvt_pk_bf16_f32 v207, v100, v101
	s_waitcnt lgkmcnt(7)
	s_nop 0
	v_mfma_f32_32x32x16_bf16 v[18:33], v[60:63], v[204:207], v[18:33]
	v_add_f32_e32 v1, v102, v103
	v_add_f32_e32 v1, v1, v104
	v_add_f32_e32 v1, v1, v105
	s_waitcnt lgkmcnt(5)
	v_mfma_f32_32x32x16_bf16 v[2:17], v[118:121], v[204:207], v[2:17]
	v_cvt_pk_bf16_f32 v60, v194, v187
	v_cvt_pk_bf16_f32 v61, v186, v185
	v_cvt_pk_bf16_f32 v62, v133, v132
	v_cvt_pk_bf16_f32 v63, v131, v130
	v_add_f32_e32 v1, v1, v98
	v_add_f32_e32 v1, v1, v99
	v_add_f32_e32 v1, v1, v100
	v_add_f32_e32 v1, v1, v101
	s_nop 0
	v_mfma_f32_32x32x16_bf16 v[18:33], v[114:117], v[60:63], v[18:33]
	v_add_f32_e32 v1, v1, v194
	v_add_f32_e32 v1, v1, v187
	v_add_f32_e32 v1, v1, v186
	v_add_f32_e32 v1, v1, v185
	s_waitcnt lgkmcnt(4)
	v_mfma_f32_32x32x16_bf16 v[2:17], v[134:137], v[60:63], v[2:17]
	v_cvt_pk_bf16_f32 v98, v129, v128
	v_cvt_pk_bf16_f32 v99, v127, v126
	v_cvt_pk_bf16_f32 v100, v125, v124
	v_cvt_pk_bf16_f32 v101, v123, v122
	v_add_f32_e32 v1, v1, v133
	v_add_f32_e32 v1, v1, v132
	v_add_f32_e32 v1, v1, v131
	v_add_f32_e32 v1, v1, v130
	s_waitcnt lgkmcnt(3)
	v_mfma_f32_32x32x16_bf16 v[18:33], v[146:149], v[98:101], v[18:33]
	v_add_f32_e32 v1, v1, v129
	v_add_f32_e32 v1, v1, v128
	v_add_f32_e32 v1, v1, v127
	v_add_f32_e32 v1, v1, v126
	s_waitcnt lgkmcnt(1)
	v_mfma_f32_32x32x16_bf16 v[2:17], v[196:199], v[98:101], v[2:17]
	v_cvt_pk_bf16_f32 v60, v109, v108
	v_cvt_pk_bf16_f32 v61, v107, v106
	v_cvt_pk_bf16_f32 v62, v113, v112
	v_cvt_pk_bf16_f32 v63, v111, v110
	v_add_f32_e32 v1, v1, v125
	v_add_f32_e32 v1, v1, v124
	v_add_f32_e32 v1, v1, v123
	v_add_f32_e32 v1, v1, v122
	s_nop 0
	v_mfma_f32_32x32x16_bf16 v[18:33], v[150:153], v[60:63], v[18:33]
	v_add_f32_e32 v1, v1, v109
	v_add_f32_e32 v1, v1, v108
	v_add_f32_e32 v1, v1, v107
	v_add_f32_e32 v1, v1, v106
	s_waitcnt lgkmcnt(0)
	v_mfma_f32_32x32x16_bf16 v[2:17], v[200:203], v[60:63], v[2:17]
	v_add_f32_e32 v1, v1, v113
	v_add_f32_e32 v1, v1, v112
	v_add_f32_e32 v1, v1, v111
	v_add_f32_e32 v1, v1, v110
	s_setprio 2
	s_waitcnt lgkmcnt(0)
	s_barrier
	ds_read_b128 v[240:243], v165 offset:18432
	ds_read_b128 v[244:247], v165 offset:23040
	ds_read_b128 v[130:133], v165 offset:18464
	ds_read_b128 v[146:149], v165 offset:23072
	s_waitcnt lgkmcnt(2)
	v_mfma_f32_32x32x16_bf16 v[114:129], v[240:243], v[158:161], v[34:49]
	v_exp_f32_e32 v185, v82
	v_exp_f32_e32 v186, v83
	v_exp_f32_e32 v187, v84
	v_exp_f32_e32 v194, v85
	v_exp_f32_e32 v195, v86
	v_exp_f32_e32 v196, v87
	v_exp_f32_e32 v197, v88
	v_exp_f32_e32 v198, v89
	s_waitcnt lgkmcnt(1)
	v_mfma_f32_32x32x16_bf16 v[98:113], v[244:247], v[158:161], v[34:49]
	v_exp_f32_e32 v199, v90
	v_exp_f32_e32 v200, v91
	v_exp_f32_e32 v201, v92
	v_exp_f32_e32 v202, v93
	v_exp_f32_e32 v134, v94
	v_exp_f32_e32 v135, v95
	v_exp_f32_e32 v136, v96
	v_exp_f32_e32 v137, v97
	v_mfma_f32_32x32x16_bf16 v[114:129], v[130:133], v[154:157], v[114:129]
	v_exp_f32_e32 v96, v66
	v_exp_f32_e32 v97, v67
	v_exp_f32_e32 v203, v68
	v_exp_f32_e32 v204, v69
	v_exp_f32_e32 v130, v70
	v_exp_f32_e32 v131, v71
	v_exp_f32_e32 v132, v72
	v_exp_f32_e32 v133, v73
	s_waitcnt lgkmcnt(0)
	v_mfma_f32_32x32x16_bf16 v[98:113], v[146:149], v[154:157], v[98:113]
	v_exp_f32_e32 v205, v74
	v_exp_f32_e32 v206, v75
	v_exp_f32_e32 v207, v76
	v_exp_f32_e32 v208, v77
	v_exp_f32_e32 v209, v78
	v_exp_f32_e32 v210, v79
	v_exp_f32_e32 v211, v80
	v_exp_f32_e32 v212, v81
	s_cmp_gt_i32 s25, 2
	s_cselect_b32 s27, -3, 2
	s_add_i32 s27, s27, s25
	v_add_u32_e32 v88, s26, v163
	s_add_i32 s26, s23, -6
	s_mulk_i32 s27, 0x2400
	s_min_u32 s26, s26, s13
	v_add_u32_e32 v51, s27, v182
	s_min_u32 s24, s24, s13
	s_lshl_b32 s92, s26, 13
	s_waitcnt vmcnt(3)
	ds_write_b128 v182, v[138:141]
	s_waitcnt vmcnt(2)
	ds_write_b128 v51, v[142:145] offset:36864
	v_add_f32_e32 v1, v50, v1
	s_add_u32 vcc_lo, s100, s92
	s_addc_u32 vcc_hi, s101, 0
	global_load_dwordx4 v[146:149], v248, vcc
	s_lshl_b32 s92, s24, 7
	s_add_u32 vcc_lo, s98, s92
	s_addc_u32 vcc_hi, s99, 0
	global_load_dwordx4 v[150:153], v249, vcc
	ds_read_b128 v[240:243], v165 offset:27648
	ds_read_b128 v[244:247], v165 offset:32256
	ds_read_b128 v[60:63], v88 offset:41472
	ds_read_b128 v[64:67], v88 offset:36864
	ds_read_b128 v[68:71], v88 offset:36896
	ds_read_b128 v[72:75], v88 offset:41504
	ds_read_b128 v[76:79], v88 offset:36928
	ds_read_b128 v[80:83], v88 offset:41536
	ds_read_b128 v[84:87], v88 offset:36960
	ds_read_b128 v[88:91], v88 offset:41568
	s_add_i32 s27, s25, 1
	s_setprio 1
	v_cvt_pk_bf16_f32 v92, v185, v186
	v_cvt_pk_bf16_f32 v93, v187, v194
	v_cvt_pk_bf16_f32 v94, v195, v196
	v_cvt_pk_bf16_f32 v95, v197, v198
	s_waitcnt lgkmcnt(6)
	s_nop 0
	v_mfma_f32_32x32x16_bf16 v[18:33], v[64:67], v[92:95], v[18:33]
	v_add_f32_e32 v213, v185, v186
	v_add_f32_e32 v213, v213, v187
	v_add_f32_e32 v213, v213, v194
	s_nop 0
	v_mfma_f32_32x32x16_bf16 v[2:17], v[60:63], v[92:95], v[2:17]
	v_cvt_pk_bf16_f32 v64, v199, v200
	v_cvt_pk_bf16_f32 v65, v201, v202
	v_cvt_pk_bf16_f32 v66, v134, v135
	v_cvt_pk_bf16_f32 v67, v136, v137
	v_add_f32_e32 v213, v213, v195
	v_add_f32_e32 v213, v213, v196
	v_add_f32_e32 v213, v213, v197
	v_add_f32_e32 v213, v213, v198
	s_waitcnt lgkmcnt(5)
	v_mfma_f32_32x32x16_bf16 v[18:33], v[68:71], v[64:67], v[18:33]
	v_add_f32_e32 v213, v213, v199
	v_add_f32_e32 v213, v213, v200
	v_add_f32_e32 v213, v213, v201
	v_add_f32_e32 v213, v213, v202
	s_waitcnt lgkmcnt(4)
	v_mfma_f32_32x32x16_bf16 v[2:17], v[72:75], v[64:67], v[2:17]
	v_cvt_pk_bf16_f32 v60, v96, v97
	v_cvt_pk_bf16_f32 v61, v203, v204
	v_cvt_pk_bf16_f32 v62, v130, v131
	v_cvt_pk_bf16_f32 v63, v132, v133
	v_add_f32_e32 v213, v213, v134
	v_add_f32_e32 v213, v213, v135
	v_add_f32_e32 v213, v213, v136
	v_add_f32_e32 v213, v213, v137
	s_waitcnt lgkmcnt(3)
	v_mfma_f32_32x32x16_bf16 v[18:33], v[76:79], v[60:63], v[18:33]
	v_add_f32_e32 v213, v213, v96
	v_add_f32_e32 v213, v213, v97
	v_add_f32_e32 v213, v213, v203
	v_add_f32_e32 v213, v213, v204
	s_waitcnt lgkmcnt(2)
	v_mfma_f32_32x32x16_bf16 v[2:17], v[80:83], v[60:63], v[2:17]
	v_cvt_pk_bf16_f32 v64, v205, v206
	v_cvt_pk_bf16_f32 v65, v207, v208
	v_cvt_pk_bf16_f32 v66, v209, v210
	v_cvt_pk_bf16_f32 v67, v211, v212
	v_add_f32_e32 v213, v213, v130
	v_add_f32_e32 v213, v213, v131
	v_add_f32_e32 v213, v213, v132
	v_add_f32_e32 v213, v213, v133
	s_waitcnt lgkmcnt(1)
	v_mfma_f32_32x32x16_bf16 v[18:33], v[84:87], v[64:67], v[18:33]
	v_add_f32_e32 v213, v213, v205
	v_add_f32_e32 v213, v213, v206
	v_add_f32_e32 v213, v213, v207
	v_add_f32_e32 v213, v213, v208
	s_waitcnt lgkmcnt(0)
	v_mfma_f32_32x32x16_bf16 v[2:17], v[88:91], v[64:67], v[2:17]
	v_add_f32_e32 v213, v213, v209
	v_add_f32_e32 v213, v213, v210
	v_add_f32_e32 v213, v213, v211
	v_add_f32_e32 v213, v213, v212
	s_setprio 0
	ds_read_b128 v[64:67], v165 offset:27680
	ds_read_b128 v[72:75], v165 offset:32288
	s_cmp_lg_u32 s25, 4
	s_cselect_b32 s24, s27, 0
	s_waitcnt lgkmcnt(2)
	v_mfma_f32_32x32x16_bf16 v[130:145], v[240:243], v[158:161], v[34:49]
	v_exp_f32_e32 v185, v114
	v_exp_f32_e32 v186, v115
	v_exp_f32_e32 v187, v116
	v_exp_f32_e32 v194, v117
	v_exp_f32_e32 v195, v118
	v_exp_f32_e32 v196, v119
	v_exp_f32_e32 v197, v120
	v_exp_f32_e32 v198, v121
	s_waitcnt lgkmcnt(1)
	v_mfma_f32_32x32x16_bf16 v[82:97], v[244:247], v[158:161], v[34:49]
	v_exp_f32_e32 v199, v122
	v_exp_f32_e32 v200, v123
	v_exp_f32_e32 v201, v124
	v_exp_f32_e32 v202, v125
	v_exp_f32_e32 v122, v126
	v_exp_f32_e32 v123, v127
	v_exp_f32_e32 v124, v128
	v_exp_f32_e32 v125, v129
	v_mfma_f32_32x32x16_bf16 v[130:145], v[64:67], v[154:157], v[130:145]
	v_exp_f32_e32 v126, v98
	v_exp_f32_e32 v127, v99
	v_exp_f32_e32 v128, v100
	v_exp_f32_e32 v129, v101
	v_exp_f32_e32 v203, v102
	v_exp_f32_e32 v204, v103
	v_exp_f32_e32 v205, v104
	v_exp_f32_e32 v206, v105
	s_waitcnt lgkmcnt(0)
	v_mfma_f32_32x32x16_bf16 v[82:97], v[72:75], v[154:157], v[82:97]
	v_exp_f32_e32 v102, v106
	v_exp_f32_e32 v103, v107
	v_exp_f32_e32 v104, v108
	v_exp_f32_e32 v105, v109
	v_exp_f32_e32 v106, v110
	v_exp_f32_e32 v107, v111
	v_exp_f32_e32 v108, v112
	v_exp_f32_e32 v109, v113
	s_cmp_gt_i32 s24, 2
	s_cselect_b32 s25, -3, 2
	s_add_i32 s25, s25, s24
	s_mulk_i32 s25, 0x2400
	v_add_u32_e32 v50, s25, v182
	s_add_i32 s25, s24, 1
	s_cmp_lg_u32 s24, 4
	s_cselect_b32 s24, s25, 0
	s_add_i32 s25, s23, -5
	s_min_u32 s25, s25, s13
	s_lshl_b32 s92, s25, 13
	s_waitcnt vmcnt(3)
	ds_write_b128 v182, v[52:55] offset:9216
	s_waitcnt vmcnt(2)
	ds_write_b128 v50, v[56:59] offset:36864
	s_add_u32 vcc_lo, s100, s92
	s_addc_u32 vcc_hi, s101, 0
	global_load_dwordx4 v[118:121], v248, vcc
	s_lshl_b32 s92, s26, 7
	s_add_u32 vcc_lo, s98, s92
	s_addc_u32 vcc_hi, s99, 0
	global_load_dwordx4 v[114:117], v249, vcc
	s_mul_i32 s26, s24, 0x2400
	s_add_i32 s27, s26, 0xffffdc00
	s_cmp_lg_u32 s24, 0
	s_cselect_b32 s27, s27, 0x9000
	v_add_u32_e32 v78, s27, v163
	ds_read_b128 v[50:53], v78 offset:36864
	ds_read_b128 v[54:57], v78 offset:36896
	ds_read_b128 v[58:61], v78 offset:41472
	ds_read_b128 v[62:65], v78 offset:41504
	ds_read_b128 v[66:69], v78 offset:36928
	ds_read_b128 v[70:73], v78 offset:36960
	ds_read_b128 v[74:77], v78 offset:41536
	ds_read_b128 v[78:81], v78 offset:41568
	s_setprio 3
	v_cvt_pk_bf16_f32 v98, v185, v186
	v_cvt_pk_bf16_f32 v99, v187, v194
	v_cvt_pk_bf16_f32 v100, v195, v196
	v_cvt_pk_bf16_f32 v101, v197, v198
	s_waitcnt lgkmcnt(7)
	s_nop 0
	v_mfma_f32_32x32x16_bf16 v[18:33], v[50:53], v[98:101], v[18:33]
	v_add_f32_e32 v110, v185, v186
	v_add_f32_e32 v110, v110, v187
	v_add_f32_e32 v110, v110, v194
	s_waitcnt lgkmcnt(5)
	v_mfma_f32_32x32x16_bf16 v[2:17], v[58:61], v[98:101], v[2:17]
	v_cvt_pk_bf16_f32 v50, v199, v200
	v_cvt_pk_bf16_f32 v51, v201, v202
	v_cvt_pk_bf16_f32 v52, v122, v123
	v_cvt_pk_bf16_f32 v53, v124, v125
	v_add_f32_e32 v110, v110, v195
	v_add_f32_e32 v110, v110, v196
	v_add_f32_e32 v110, v110, v197
	v_add_f32_e32 v110, v110, v198
	s_nop 0
	v_mfma_f32_32x32x16_bf16 v[18:33], v[54:57], v[50:53], v[18:33]
	v_add_f32_e32 v110, v110, v199
	v_add_f32_e32 v110, v110, v200
	v_add_f32_e32 v110, v110, v201
	v_add_f32_e32 v110, v110, v202
	s_waitcnt lgkmcnt(4)
	v_mfma_f32_32x32x16_bf16 v[2:17], v[62:65], v[50:53], v[2:17]
	v_cvt_pk_bf16_f32 v54, v126, v127
	v_cvt_pk_bf16_f32 v55, v128, v129
	v_cvt_pk_bf16_f32 v56, v203, v204
	v_cvt_pk_bf16_f32 v57, v205, v206
	v_add_f32_e32 v110, v110, v122
	v_add_f32_e32 v110, v110, v123
	v_add_f32_e32 v110, v110, v124
	v_add_f32_e32 v110, v110, v125
	s_waitcnt lgkmcnt(3)
	v_mfma_f32_32x32x16_bf16 v[18:33], v[66:69], v[54:57], v[18:33]
	v_add_f32_e32 v110, v110, v126
	v_add_f32_e32 v110, v110, v127
	v_add_f32_e32 v110, v110, v128
	v_add_f32_e32 v110, v110, v129
	s_waitcnt lgkmcnt(1)
	v_mfma_f32_32x32x16_bf16 v[2:17], v[74:77], v[54:57], v[2:17]
	v_cvt_pk_bf16_f32 v50, v102, v103
	v_cvt_pk_bf16_f32 v51, v104, v105
	v_cvt_pk_bf16_f32 v52, v106, v107
	v_cvt_pk_bf16_f32 v53, v108, v109
	v_add_f32_e32 v110, v110, v203
	v_add_f32_e32 v110, v110, v204
	v_add_f32_e32 v110, v110, v205
	v_add_f32_e32 v110, v110, v206
	s_nop 0
	v_mfma_f32_32x32x16_bf16 v[18:33], v[70:73], v[50:53], v[18:33]
	v_add_f32_e32 v110, v110, v102
	v_add_f32_e32 v110, v110, v103
	v_add_f32_e32 v110, v110, v104
	v_add_f32_e32 v110, v110, v105
	s_waitcnt lgkmcnt(0)
	v_mfma_f32_32x32x16_bf16 v[2:17], v[78:81], v[50:53], v[2:17]
	v_add_f32_e32 v110, v110, v106
	v_add_f32_e32 v110, v110, v107
	v_add_f32_e32 v110, v110, v108
	v_add_f32_e32 v110, v110, v109
	s_setprio 2
	s_waitcnt lgkmcnt(0)
	s_barrier
	ds_read_b128 v[240:243], v165
	ds_read_b128 v[244:247], v165 offset:4608
	ds_read_b128 v[102:105], v165 offset:32
	ds_read_b128 v[106:109], v165 offset:4640
	v_add_f32_e32 v1, v1, v213
	s_waitcnt lgkmcnt(2)
	v_mfma_f32_32x32x16_bf16 v[66:81], v[240:243], v[158:161], v[34:49]
	v_exp_f32_e32 v185, v130
	v_exp_f32_e32 v186, v131
	v_exp_f32_e32 v187, v132
	v_exp_f32_e32 v194, v133
	v_exp_f32_e32 v195, v134
	v_exp_f32_e32 v196, v135
	v_exp_f32_e32 v197, v136
	v_exp_f32_e32 v198, v137
	v_mfma_f32_32x32x16_bf16 v[50:65], v[244:247], v[158:161], v[34:49]
	v_exp_f32_e32 v134, v138
	v_exp_f32_e32 v135, v139
	v_exp_f32_e32 v136, v140
	v_exp_f32_e32 v137, v141
	v_exp_f32_e32 v138, v142
	v_exp_f32_e32 v139, v143
	v_exp_f32_e32 v140, v144
	v_exp_f32_e32 v141, v145
	s_waitcnt lgkmcnt(1)
	v_mfma_f32_32x32x16_bf16 v[66:81], v[102:105], v[154:157], v[66:81]
	v_exp_f32_e32 v142, v82
	v_exp_f32_e32 v143, v83
	v_exp_f32_e32 v144, v84
	v_exp_f32_e32 v145, v85
	v_exp_f32_e32 v199, v86
	v_exp_f32_e32 v200, v87
	v_exp_f32_e32 v201, v88
	v_exp_f32_e32 v202, v89
	s_waitcnt lgkmcnt(0)
	v_mfma_f32_32x32x16_bf16 v[50:65], v[106:109], v[154:157], v[50:65]
	v_exp_f32_e32 v203, v90
	v_exp_f32_e32 v204, v91
	v_exp_f32_e32 v205, v92
	v_exp_f32_e32 v206, v93
	v_exp_f32_e32 v207, v94
	v_exp_f32_e32 v208, v95
	v_exp_f32_e32 v209, v96
	v_exp_f32_e32 v210, v97
	s_cmp_gt_i32 s24, 2
	s_cselect_b32 s27, -3, 2
	s_add_i32 s27, s27, s24
	s_mulk_i32 s27, 0x2400
	v_add_u32_e32 v82, s27, v182
	s_mov_b32 s27, 0x18950000
	s_waitcnt vmcnt(3)
	ds_write_b128 v182, v[146:149] offset:18432
	s_waitcnt vmcnt(2)
	ds_write_b128 v82, v[150:153] offset:36864
	s_add_i32 s92, s23, -4
	s_lshl_b32 s92, s92, 13
	s_add_u32 vcc_lo, s100, s92
	s_addc_u32 vcc_hi, s101, 0
	global_load_dwordx4 v[126:129], v248, vcc
	s_lshl_b32 s92, s25, 7
	s_add_u32 vcc_lo, s98, s92
	s_addc_u32 vcc_hi, s99, 0
	global_load_dwordx4 v[122:125], v249, vcc
	v_add_u32_e32 v111, s26, v163
	v_add_f32_e32 v1, v1, v110
	ds_read_b128 v[240:243], v165 offset:9216
	ds_read_b128 v[244:247], v165 offset:13824
	ds_read_b128 v[82:85], v111 offset:41472
	ds_read_b128 v[86:89], v111 offset:36864
	ds_read_b128 v[90:93], v111 offset:36896
	ds_read_b128 v[94:97], v111 offset:41504
	ds_read_b128 v[98:101], v111 offset:36928
	ds_read_b128 v[102:105], v111 offset:41536
	ds_read_b128 v[106:109], v111 offset:36960
	ds_read_b128 v[110:113], v111 offset:41568
	s_add_i32 s26, s24, 1
	s_setprio 1
	v_cvt_pk_bf16_f32 v130, v185, v186
	v_cvt_pk_bf16_f32 v131, v187, v194
	v_cvt_pk_bf16_f32 v132, v195, v196
	v_cvt_pk_bf16_f32 v133, v197, v198
	s_waitcnt lgkmcnt(6)
	s_nop 0
	v_mfma_f32_32x32x16_bf16 v[18:33], v[86:89], v[130:133], v[18:33]
	v_add_f32_e32 v146, v185, v186
	v_add_f32_e32 v146, v146, v187
	v_add_f32_e32 v146, v146, v194
	s_nop 0
	v_mfma_f32_32x32x16_bf16 v[2:17], v[82:85], v[130:133], v[2:17]
	v_cvt_pk_bf16_f32 v86, v134, v135
	v_cvt_pk_bf16_f32 v87, v136, v137
	v_cvt_pk_bf16_f32 v88, v138, v139
	v_cvt_pk_bf16_f32 v89, v140, v141
	v_add_f32_e32 v146, v146, v195
	v_add_f32_e32 v146, v146, v196
	v_add_f32_e32 v146, v146, v197
	v_add_f32_e32 v146, v146, v198
	s_waitcnt lgkmcnt(5)
	v_mfma_f32_32x32x16_bf16 v[18:33], v[90:93], v[86:89], v[18:33]
	v_add_f32_e32 v146, v146, v134
	v_add_f32_e32 v146, v146, v135
	v_add_f32_e32 v146, v146, v136
	v_add_f32_e32 v146, v146, v137
	s_waitcnt lgkmcnt(4)
	v_mfma_f32_32x32x16_bf16 v[2:17], v[94:97], v[86:89], v[2:17]
	v_cvt_pk_bf16_f32 v82, v142, v143
	v_cvt_pk_bf16_f32 v83, v144, v145
	v_cvt_pk_bf16_f32 v84, v199, v200
	v_cvt_pk_bf16_f32 v85, v201, v202
	v_add_f32_e32 v146, v146, v138
	v_add_f32_e32 v146, v146, v139
	v_add_f32_e32 v146, v146, v140
	v_add_f32_e32 v146, v146, v141
	s_waitcnt lgkmcnt(3)
	v_mfma_f32_32x32x16_bf16 v[18:33], v[98:101], v[82:85], v[18:33]
	v_add_f32_e32 v146, v146, v142
	v_add_f32_e32 v146, v146, v143
	v_add_f32_e32 v146, v146, v144
	v_add_f32_e32 v146, v146, v145
	s_waitcnt lgkmcnt(2)
	v_mfma_f32_32x32x16_bf16 v[2:17], v[102:105], v[82:85], v[2:17]
	v_cvt_pk_bf16_f32 v86, v203, v204
	v_cvt_pk_bf16_f32 v87, v205, v206
	v_cvt_pk_bf16_f32 v88, v207, v208
	v_cvt_pk_bf16_f32 v89, v209, v210
	v_add_f32_e32 v146, v146, v199
	v_add_f32_e32 v146, v146, v200
	v_add_f32_e32 v146, v146, v201
	v_add_f32_e32 v146, v146, v202
	s_waitcnt lgkmcnt(1)
	v_mfma_f32_32x32x16_bf16 v[18:33], v[106:109], v[86:89], v[18:33]
	v_add_f32_e32 v146, v146, v203
	v_add_f32_e32 v146, v146, v204
	v_add_f32_e32 v146, v146, v205
	v_add_f32_e32 v146, v146, v206
	s_waitcnt lgkmcnt(0)
	v_mfma_f32_32x32x16_bf16 v[2:17], v[110:113], v[86:89], v[2:17]
	v_add_f32_e32 v146, v146, v207
	v_add_f32_e32 v146, v146, v208
	v_add_f32_e32 v146, v146, v209
	v_add_f32_e32 v146, v146, v210
	s_setprio 0
	ds_read_b128 v[130:133], v165 offset:9248
	ds_read_b128 v[138:141], v165 offset:13856
	s_cmp_lg_u32 s24, 4
	s_cselect_b32 s24, s26, 0
	s_waitcnt lgkmcnt(2)
	v_mfma_f32_32x32x16_bf16 v[98:113], v[240:243], v[158:161], v[34:49]
	v_exp_f32_e32 v142, v66
	v_exp_f32_e32 v143, v67
	v_exp_f32_e32 v144, v68
	v_exp_f32_e32 v145, v69
	v_exp_f32_e32 v147, v70
	v_exp_f32_e32 v148, v71
	v_exp_f32_e32 v149, v72
	v_exp_f32_e32 v150, v73
	s_waitcnt lgkmcnt(1)
	v_mfma_f32_32x32x16_bf16 v[82:97], v[244:247], v[158:161], v[34:49]
	v_exp_f32_e32 v151, v74
	v_exp_f32_e32 v152, v75
	v_exp_f32_e32 v153, v76
	v_exp_f32_e32 v178, v77
	v_exp_f32_e32 v134, v78
	v_exp_f32_e32 v135, v79
	v_exp_f32_e32 v136, v80
	v_exp_f32_e32 v137, v81
	v_mfma_f32_32x32x16_bf16 v[98:113], v[130:133], v[154:157], v[98:113]
	v_exp_f32_e32 v179, v50
	v_exp_f32_e32 v185, v51
	v_exp_f32_e32 v186, v52
	v_exp_f32_e32 v187, v53
	v_exp_f32_e32 v194, v54
	v_exp_f32_e32 v195, v55
	v_exp_f32_e32 v196, v56
	v_exp_f32_e32 v197, v57
	s_waitcnt lgkmcnt(0)
	v_mfma_f32_32x32x16_bf16 v[82:97], v[138:141], v[154:157], v[82:97]
	v_exp_f32_e32 v198, v58
	v_exp_f32_e32 v199, v59
	v_exp_f32_e32 v200, v60
	v_exp_f32_e32 v201, v61
	v_exp_f32_e32 v138, v62
	v_exp_f32_e32 v139, v63
	v_exp_f32_e32 v140, v64
	v_exp_f32_e32 v141, v65
	s_cmp_gt_i32 s24, 2
	s_cselect_b32 s25, -3, 2
	s_add_i32 s25, s25, s24
	s_mulk_i32 s25, 0x2400
	v_add_u32_e32 v50, s25, v182
	s_add_i32 s25, s24, 1
	s_cmp_lg_u32 s24, 4
	s_cselect_b32 s25, s25, 0
	s_add_i32 s24, s23, -3
	s_min_u32 s26, s24, s13
	s_lshl_b32 s92, s26, 13
	s_waitcnt vmcnt(3)
	ds_write_b128 v182, v[118:121] offset:27648
	s_waitcnt vmcnt(2)
	ds_write_b128 v50, v[114:117] offset:36864
	s_add_u32 vcc_lo, s100, s92
	s_addc_u32 vcc_hi, s101, 0
	global_load_dwordx4 v[118:121], v248, vcc
	s_add_i32 s92, s23, -4
	s_lshl_b32 s92, s92, 7
	s_add_u32 vcc_lo, s98, s92
	s_addc_u32 vcc_hi, s99, 0
	global_load_dwordx4 v[114:117], v249, vcc
	s_mul_i32 s27, s25, 0x2400
	s_add_i32 s28, s27, 0xffffdc00
	s_cmp_lg_u32 s25, 0
	s_cselect_b32 s28, s28, 0x9000
	v_add_u32_e32 v78, s28, v163
	ds_read_b128 v[50:53], v78 offset:36864
	ds_read_b128 v[54:57], v78 offset:36896
	ds_read_b128 v[58:61], v78 offset:41472
	ds_read_b128 v[62:65], v78 offset:41504
	ds_read_b128 v[66:69], v78 offset:36928
	ds_read_b128 v[70:73], v78 offset:36960
	ds_read_b128 v[74:77], v78 offset:41536
	ds_read_b128 v[78:81], v78 offset:41568
	s_setprio 3
	v_cvt_pk_bf16_f32 v130, v142, v143
	v_cvt_pk_bf16_f32 v131, v144, v145
	v_cvt_pk_bf16_f32 v132, v147, v148
	v_cvt_pk_bf16_f32 v133, v149, v150
	s_waitcnt lgkmcnt(7)
	s_nop 0
	v_mfma_f32_32x32x16_bf16 v[18:33], v[50:53], v[130:133], v[18:33]
	v_add_f32_e32 v176, v142, v143
	v_add_f32_e32 v176, v176, v144
	v_add_f32_e32 v176, v176, v145
	s_waitcnt lgkmcnt(5)
	v_mfma_f32_32x32x16_bf16 v[2:17], v[58:61], v[130:133], v[2:17]
	v_cvt_pk_bf16_f32 v50, v151, v152
	v_cvt_pk_bf16_f32 v51, v153, v178
	v_cvt_pk_bf16_f32 v52, v134, v135
	v_cvt_pk_bf16_f32 v53, v136, v137
	v_add_f32_e32 v176, v176, v147
	v_add_f32_e32 v176, v176, v148
	v_add_f32_e32 v176, v176, v149
	v_add_f32_e32 v176, v176, v150
	s_nop 0
	v_mfma_f32_32x32x16_bf16 v[18:33], v[54:57], v[50:53], v[18:33]
	v_add_f32_e32 v176, v176, v151
	v_add_f32_e32 v176, v176, v152
	v_add_f32_e32 v176, v176, v153
	v_add_f32_e32 v176, v176, v178
	s_waitcnt lgkmcnt(4)
	v_mfma_f32_32x32x16_bf16 v[2:17], v[62:65], v[50:53], v[2:17]
	v_cvt_pk_bf16_f32 v54, v179, v185
	v_cvt_pk_bf16_f32 v55, v186, v187
	v_cvt_pk_bf16_f32 v56, v194, v195
	v_cvt_pk_bf16_f32 v57, v196, v197
	v_add_f32_e32 v176, v176, v134
	v_add_f32_e32 v176, v176, v135
	v_add_f32_e32 v176, v176, v136
	v_add_f32_e32 v176, v176, v137
	s_waitcnt lgkmcnt(3)
	v_mfma_f32_32x32x16_bf16 v[18:33], v[66:69], v[54:57], v[18:33]
	v_add_f32_e32 v176, v176, v179
	v_add_f32_e32 v176, v176, v185
	v_add_f32_e32 v176, v176, v186
	v_add_f32_e32 v176, v176, v187
	s_waitcnt lgkmcnt(1)
	v_mfma_f32_32x32x16_bf16 v[2:17], v[74:77], v[54:57], v[2:17]
	v_cvt_pk_bf16_f32 v50, v198, v199
	v_cvt_pk_bf16_f32 v51, v200, v201
	v_cvt_pk_bf16_f32 v52, v138, v139
	v_cvt_pk_bf16_f32 v53, v140, v141
	v_add_f32_e32 v176, v176, v194
	v_add_f32_e32 v176, v176, v195
	v_add_f32_e32 v176, v176, v196
	v_add_f32_e32 v176, v176, v197
	s_nop 0
	v_mfma_f32_32x32x16_bf16 v[18:33], v[70:73], v[50:53], v[18:33]
	v_add_f32_e32 v176, v176, v198
	v_add_f32_e32 v176, v176, v199
	v_add_f32_e32 v176, v176, v200
	v_add_f32_e32 v176, v176, v201
	s_waitcnt lgkmcnt(0)
	v_mfma_f32_32x32x16_bf16 v[2:17], v[78:81], v[50:53], v[2:17]
	v_add_f32_e32 v176, v176, v138
	v_add_f32_e32 v176, v176, v139
	v_add_f32_e32 v176, v176, v140
	v_add_f32_e32 v176, v176, v141
	s_setprio 2
	s_waitcnt lgkmcnt(0)
	s_barrier
	ds_read_b128 v[240:243], v165 offset:18432
	ds_read_b128 v[244:247], v165 offset:23040
	ds_read_b128 v[134:137], v165 offset:18464
	ds_read_b128 v[138:141], v165 offset:23072
	v_add_f32_e32 v1, v1, v146
	s_waitcnt lgkmcnt(2)
	v_mfma_f32_32x32x16_bf16 v[66:81], v[240:243], v[158:161], v[34:49]
	v_exp_f32_e32 v142, v98
	v_exp_f32_e32 v143, v99
	v_exp_f32_e32 v144, v100
	v_exp_f32_e32 v145, v101
	v_exp_f32_e32 v146, v102
	v_exp_f32_e32 v147, v103
	v_exp_f32_e32 v148, v104
	v_exp_f32_e32 v149, v105
	v_mfma_f32_32x32x16_bf16 v[50:65], v[244:247], v[158:161], v[34:49]
	v_exp_f32_e32 v150, v106
	v_exp_f32_e32 v151, v107
	v_exp_f32_e32 v152, v108
	v_exp_f32_e32 v153, v109
	v_exp_f32_e32 v177, v110
	v_exp_f32_e32 v178, v111
	v_exp_f32_e32 v179, v112
	v_exp_f32_e32 v185, v113
	s_waitcnt lgkmcnt(1)
	v_mfma_f32_32x32x16_bf16 v[66:81], v[134:137], v[154:157], v[66:81]
	v_exp_f32_e32 v186, v82
	v_exp_f32_e32 v187, v83
	v_exp_f32_e32 v194, v84
	v_exp_f32_e32 v195, v85
	v_exp_f32_e32 v134, v86
	v_exp_f32_e32 v135, v87
	v_exp_f32_e32 v136, v88
	v_exp_f32_e32 v137, v89
	s_waitcnt lgkmcnt(0)
	v_mfma_f32_32x32x16_bf16 v[50:65], v[138:141], v[154:157], v[50:65]
	v_exp_f32_e32 v196, v90
	v_exp_f32_e32 v197, v91
	v_exp_f32_e32 v198, v92
	v_exp_f32_e32 v199, v93
	v_exp_f32_e32 v138, v94
	v_exp_f32_e32 v139, v95
	v_exp_f32_e32 v140, v96
	v_exp_f32_e32 v141, v97
	s_cmp_gt_i32 s25, 2
	s_cselect_b32 s28, -3, 2
	s_waitcnt vmcnt(3)
	ds_write_b128 v182, v[126:129]
	s_add_i32 s28, s28, s25
	v_add_u32_e32 v126, s27, v163
	s_add_i32 s27, s23, -2
	s_mulk_i32 s28, 0x2400
	s_min_u32 s27, s27, s13
	v_add_u32_e32 v82, s28, v182
	s_lshl_b32 s92, s27, 13
	s_waitcnt vmcnt(2)
	ds_write_b128 v82, v[122:125] offset:36864
	s_add_u32 vcc_lo, s100, s92
	s_addc_u32 vcc_hi, s101, 0
	global_load_dwordx4 v[98:101], v248, vcc
	s_lshl_b32 s92, s26, 7
	s_add_u32 vcc_lo, s98, s92
	s_addc_u32 vcc_hi, s99, 0
	global_load_dwordx4 v[102:105], v249, vcc
	ds_read_b128 v[240:243], v165 offset:27648
	ds_read_b128 v[244:247], v165 offset:32256
	ds_read_b128 v[82:85], v126 offset:41472
	ds_read_b128 v[86:89], v126 offset:36864
	ds_read_b128 v[90:93], v126 offset:36896
	ds_read_b128 v[94:97], v126 offset:41504
	ds_read_b128 v[106:109], v126 offset:36928
	ds_read_b128 v[110:113], v126 offset:41536
	ds_read_b128 v[122:125], v126 offset:36960
	ds_read_b128 v[126:129], v126 offset:41568
	v_add_f32_e32 v1, v1, v176
	s_add_i32 s28, s25, 1
	s_setprio 1
	v_cvt_pk_bf16_f32 v130, v142, v143
	v_cvt_pk_bf16_f32 v131, v144, v145
	v_cvt_pk_bf16_f32 v132, v146, v147
	v_cvt_pk_bf16_f32 v133, v148, v149
	s_waitcnt lgkmcnt(6)
	s_nop 0
	v_mfma_f32_32x32x16_bf16 v[18:33], v[86:89], v[130:133], v[18:33]
	v_add_f32_e32 v176, v142, v143
	v_add_f32_e32 v176, v176, v144
	v_add_f32_e32 v176, v176, v145
	s_nop 0
	v_mfma_f32_32x32x16_bf16 v[2:17], v[82:85], v[130:133], v[2:17]
	v_cvt_pk_bf16_f32 v86, v150, v151
	v_cvt_pk_bf16_f32 v87, v152, v153
	v_cvt_pk_bf16_f32 v88, v177, v178
	v_cvt_pk_bf16_f32 v89, v179, v185
	v_add_f32_e32 v176, v176, v146
	v_add_f32_e32 v176, v176, v147
	v_add_f32_e32 v176, v176, v148
	v_add_f32_e32 v176, v176, v149
	s_waitcnt lgkmcnt(5)
	v_mfma_f32_32x32x16_bf16 v[18:33], v[90:93], v[86:89], v[18:33]
	v_add_f32_e32 v176, v176, v150
	v_add_f32_e32 v176, v176, v151
	v_add_f32_e32 v176, v176, v152
	v_add_f32_e32 v176, v176, v153
	s_waitcnt lgkmcnt(4)
	v_mfma_f32_32x32x16_bf16 v[2:17], v[94:97], v[86:89], v[2:17]
	v_cvt_pk_bf16_f32 v82, v186, v187
	v_cvt_pk_bf16_f32 v83, v194, v195
	v_cvt_pk_bf16_f32 v84, v134, v135
	v_cvt_pk_bf16_f32 v85, v136, v137
	v_add_f32_e32 v176, v176, v177
	v_add_f32_e32 v176, v176, v178
	v_add_f32_e32 v176, v176, v179
	v_add_f32_e32 v176, v176, v185
	s_waitcnt lgkmcnt(3)
	v_mfma_f32_32x32x16_bf16 v[18:33], v[106:109], v[82:85], v[18:33]
	v_add_f32_e32 v176, v176, v186
	v_add_f32_e32 v176, v176, v187
	v_add_f32_e32 v176, v176, v194
	v_add_f32_e32 v176, v176, v195
	s_waitcnt lgkmcnt(2)
	v_mfma_f32_32x32x16_bf16 v[2:17], v[110:113], v[82:85], v[2:17]
	v_cvt_pk_bf16_f32 v86, v196, v197
	v_cvt_pk_bf16_f32 v87, v198, v199
	v_cvt_pk_bf16_f32 v88, v138, v139
	v_cvt_pk_bf16_f32 v89, v140, v141
	v_add_f32_e32 v176, v176, v134
	v_add_f32_e32 v176, v176, v135
	v_add_f32_e32 v176, v176, v136
	v_add_f32_e32 v176, v176, v137
	s_waitcnt lgkmcnt(1)
	v_mfma_f32_32x32x16_bf16 v[18:33], v[122:125], v[86:89], v[18:33]
	v_add_f32_e32 v176, v176, v196
	v_add_f32_e32 v176, v176, v197
	v_add_f32_e32 v176, v176, v198
	v_add_f32_e32 v176, v176, v199
	s_waitcnt lgkmcnt(0)
	v_mfma_f32_32x32x16_bf16 v[2:17], v[126:129], v[86:89], v[2:17]
	v_add_f32_e32 v176, v176, v138
	v_add_f32_e32 v176, v176, v139
	v_add_f32_e32 v176, v176, v140
	v_add_f32_e32 v176, v176, v141
	s_setprio 0
	ds_read_b128 v[106:109], v165 offset:27680
	ds_read_b128 v[122:125], v165 offset:32288
	s_cmp_lg_u32 s25, 4
	s_cselect_b32 s25, s28, 0
	s_waitcnt lgkmcnt(2)
	v_mfma_f32_32x32x16_bf16 v[138:153], v[240:243], v[158:161], v[34:49]
	v_exp_f32_e32 v126, v66
	v_exp_f32_e32 v127, v67
	v_exp_f32_e32 v128, v68
	v_exp_f32_e32 v129, v69
	v_exp_f32_e32 v130, v70
	v_exp_f32_e32 v131, v71
	v_exp_f32_e32 v132, v72
	v_exp_f32_e32 v133, v73
	s_waitcnt lgkmcnt(1)
	v_mfma_f32_32x32x16_bf16 v[82:97], v[244:247], v[158:161], v[34:49]
	v_exp_f32_e32 v134, v74
	v_exp_f32_e32 v135, v75
	v_exp_f32_e32 v136, v76
	v_exp_f32_e32 v137, v77
	v_exp_f32_e32 v177, v78
	v_exp_f32_e32 v178, v79
	v_exp_f32_e32 v179, v80
	v_exp_f32_e32 v185, v81
	v_mfma_f32_32x32x16_bf16 v[138:153], v[106:109], v[154:157], v[138:153]
	v_exp_f32_e32 v80, v50
	v_exp_f32_e32 v81, v51
	v_exp_f32_e32 v186, v52
	v_exp_f32_e32 v187, v53
	v_exp_f32_e32 v194, v54
	v_exp_f32_e32 v195, v55
	v_exp_f32_e32 v196, v56
	v_exp_f32_e32 v197, v57
	s_waitcnt lgkmcnt(0)
	v_mfma_f32_32x32x16_bf16 v[82:97], v[122:125], v[154:157], v[82:97]
	v_exp_f32_e32 v198, v58
	v_exp_f32_e32 v199, v59
	v_exp_f32_e32 v200, v60
	v_exp_f32_e32 v201, v61
	v_exp_f32_e32 v122, v62
	v_exp_f32_e32 v123, v63
	v_exp_f32_e32 v124, v64
	v_exp_f32_e32 v125, v65
	s_cmp_gt_i32 s25, 2
	s_cselect_b32 s26, -3, 2
	s_add_i32 s26, s26, s25
	s_mulk_i32 s26, 0x2400
	v_add_u32_e32 v50, s26, v182
	s_add_i32 s26, s25, 1
	s_cmp_lg_u32 s25, 4
	s_cselect_b32 s25, s26, 0
	s_add_i32 s26, s23, -1
	s_min_u32 s26, s26, s13
	s_lshl_b32 s92, s26, 13
	s_waitcnt vmcnt(3)
	ds_write_b128 v182, v[118:121] offset:9216
	s_waitcnt vmcnt(2)
	ds_write_b128 v50, v[114:117] offset:36864
	s_add_u32 vcc_lo, s100, s92
	s_addc_u32 vcc_hi, s101, 0
	global_load_dwordx4 v[56:59], v248, vcc
	s_lshl_b32 s92, s27, 7
	s_add_u32 vcc_lo, s98, s92
	s_addc_u32 vcc_hi, s99, 0
	global_load_dwordx4 v[52:55], v249, vcc
	s_nop 0
	s_mul_i32 s27, s25, 0x2400
	s_add_i32 s28, s27, 0xffffdc00
	s_cmp_lg_u32 s25, 0
	s_cselect_b32 s28, s28, 0x9000
	v_add_u32_e32 v50, s28, v163
	ds_read_b128 v[60:63], v50 offset:36864
	ds_read_b128 v[64:67], v50 offset:36896
	ds_read_b128 v[68:71], v50 offset:41472
	ds_read_b128 v[72:75], v50 offset:41504
	ds_read_b128 v[76:79], v50 offset:36928
	ds_read_b128 v[106:109], v50 offset:36960
	ds_read_b128 v[110:113], v50 offset:41536
	ds_read_b128 v[114:117], v50 offset:41568
	s_setprio 3
	v_cvt_pk_bf16_f32 v118, v126, v127
	v_cvt_pk_bf16_f32 v119, v128, v129
	v_cvt_pk_bf16_f32 v120, v130, v131
	v_cvt_pk_bf16_f32 v121, v132, v133
	s_waitcnt lgkmcnt(7)
	s_nop 0
	v_mfma_f32_32x32x16_bf16 v[18:33], v[60:63], v[118:121], v[18:33]
	v_add_f32_e32 v50, v126, v127
	v_add_f32_e32 v50, v50, v128
	v_add_f32_e32 v50, v50, v129
	s_waitcnt lgkmcnt(5)
	v_mfma_f32_32x32x16_bf16 v[2:17], v[68:71], v[118:121], v[2:17]
	v_cvt_pk_bf16_f32 v60, v134, v135
	v_cvt_pk_bf16_f32 v61, v136, v137
	v_cvt_pk_bf16_f32 v62, v177, v178
	v_cvt_pk_bf16_f32 v63, v179, v185
	v_add_f32_e32 v50, v50, v130
	v_add_f32_e32 v50, v50, v131
	v_add_f32_e32 v50, v50, v132
	v_add_f32_e32 v50, v50, v133
	s_nop 0
	v_mfma_f32_32x32x16_bf16 v[18:33], v[64:67], v[60:63], v[18:33]
	v_add_f32_e32 v50, v50, v134
	v_add_f32_e32 v50, v50, v135
	v_add_f32_e32 v50, v50, v136
	v_add_f32_e32 v50, v50, v137
	s_waitcnt lgkmcnt(4)
	v_mfma_f32_32x32x16_bf16 v[2:17], v[72:75], v[60:63], v[2:17]
	v_cvt_pk_bf16_f32 v64, v80, v81
	v_cvt_pk_bf16_f32 v65, v186, v187
	v_cvt_pk_bf16_f32 v66, v194, v195
	v_cvt_pk_bf16_f32 v67, v196, v197
	v_add_f32_e32 v50, v50, v177
	v_add_f32_e32 v50, v50, v178
	v_add_f32_e32 v50, v50, v179
	v_add_f32_e32 v50, v50, v185
	s_waitcnt lgkmcnt(3)
	v_mfma_f32_32x32x16_bf16 v[18:33], v[76:79], v[64:67], v[18:33]
	v_add_f32_e32 v50, v50, v80
	v_add_f32_e32 v50, v50, v81
	v_add_f32_e32 v50, v50, v186
	v_add_f32_e32 v50, v50, v187
	s_waitcnt lgkmcnt(1)
	v_mfma_f32_32x32x16_bf16 v[2:17], v[110:113], v[64:67], v[2:17]
	v_cvt_pk_bf16_f32 v60, v198, v199
	v_cvt_pk_bf16_f32 v61, v200, v201
	v_cvt_pk_bf16_f32 v62, v122, v123
	v_cvt_pk_bf16_f32 v63, v124, v125
	v_add_f32_e32 v50, v50, v194
	v_add_f32_e32 v50, v50, v195
	v_add_f32_e32 v50, v50, v196
	v_add_f32_e32 v50, v50, v197
	s_nop 0
	v_mfma_f32_32x32x16_bf16 v[18:33], v[106:109], v[60:63], v[18:33]
	v_add_f32_e32 v50, v50, v198
	v_add_f32_e32 v50, v50, v199
	v_add_f32_e32 v50, v50, v200
	v_add_f32_e32 v50, v50, v201
	s_waitcnt lgkmcnt(0)
	v_mfma_f32_32x32x16_bf16 v[2:17], v[114:117], v[60:63], v[2:17]
	v_add_f32_e32 v50, v50, v122
	v_add_f32_e32 v50, v50, v123
	v_add_f32_e32 v50, v50, v124
	v_add_f32_e32 v50, v50, v125
	s_setprio 2
	s_waitcnt lgkmcnt(0)
	s_barrier
	ds_read_b128 v[240:243], v165
	ds_read_b128 v[244:247], v165 offset:4608
	ds_read_b128 v[68:71], v165 offset:32
	ds_read_b128 v[72:75], v165 offset:4640
	v_add_f32_e32 v1, v1, v176
	s_waitcnt lgkmcnt(2)
	v_mfma_f32_32x32x16_bf16 v[122:137], v[240:243], v[158:161], v[34:49]
	v_exp_f32_e32 v176, v138
	v_exp_f32_e32 v177, v139
	v_exp_f32_e32 v178, v140
	v_exp_f32_e32 v179, v141
	v_exp_f32_e32 v185, v142
	v_exp_f32_e32 v186, v143
	v_exp_f32_e32 v187, v144
	v_exp_f32_e32 v194, v145
	v_mfma_f32_32x32x16_bf16 v[106:121], v[244:247], v[158:161], v[34:49]
	v_exp_f32_e32 v195, v146
	v_exp_f32_e32 v196, v147
	v_exp_f32_e32 v197, v148
	v_exp_f32_e32 v198, v149
	v_exp_f32_e32 v146, v150
	v_exp_f32_e32 v147, v151
	v_exp_f32_e32 v148, v152
	v_exp_f32_e32 v149, v153
	s_waitcnt lgkmcnt(1)
	v_mfma_f32_32x32x16_bf16 v[122:137], v[68:71], v[154:157], v[122:137]
	v_exp_f32_e32 v150, v82
	v_exp_f32_e32 v151, v83
	v_exp_f32_e32 v152, v84
	v_exp_f32_e32 v153, v85
	v_exp_f32_e32 v199, v86
	v_exp_f32_e32 v200, v87
	v_exp_f32_e32 v201, v88
	v_exp_f32_e32 v202, v89
	s_waitcnt lgkmcnt(0)
	v_mfma_f32_32x32x16_bf16 v[106:121], v[72:75], v[154:157], v[106:121]
	v_exp_f32_e32 v203, v90
	v_exp_f32_e32 v204, v91
	v_exp_f32_e32 v205, v92
	v_exp_f32_e32 v206, v93
	v_exp_f32_e32 v207, v94
	v_exp_f32_e32 v208, v95
	v_exp_f32_e32 v209, v96
	v_exp_f32_e32 v210, v97
	s_cmp_gt_i32 s25, 2
	s_cselect_b32 s28, -3, 2
	s_add_i32 s28, s28, s25
	s_mulk_i32 s28, 0x2400
	v_add_u32_e32 v88, s27, v163
	s_min_u32 s27, s23, s13
	v_add_u32_e32 v51, s28, v182
	s_lshl_b32 s92, s27, 13
	s_waitcnt vmcnt(3)
	ds_write_b128 v182, v[98:101] offset:18432
	s_waitcnt vmcnt(2)
	ds_write_b128 v51, v[102:105] offset:36864
	v_add_f32_e32 v1, v1, v50
	s_add_u32 vcc_lo, s100, s92
	s_addc_u32 vcc_hi, s101, 0
	global_load_dwordx4 v[138:141], v248, vcc
	s_lshl_b32 s92, s26, 7
	s_add_u32 vcc_lo, s98, s92
	s_addc_u32 vcc_hi, s99, 0
	global_load_dwordx4 v[142:145], v249, vcc
	ds_read_b128 v[240:243], v165 offset:9216
	ds_read_b128 v[244:247], v165 offset:13824
	ds_read_b128 v[60:63], v88 offset:41472
	ds_read_b128 v[64:67], v88 offset:36864
	ds_read_b128 v[68:71], v88 offset:36896
	ds_read_b128 v[72:75], v88 offset:41504
	ds_read_b128 v[76:79], v88 offset:36928
	ds_read_b128 v[80:83], v88 offset:41536
	ds_read_b128 v[84:87], v88 offset:36960
	ds_read_b128 v[88:91], v88 offset:41568
	s_setprio 1
	v_mov_b32_e32 v51, v122
	v_cvt_pk_bf16_f32 v92, v176, v177
	v_cvt_pk_bf16_f32 v93, v178, v179
	v_cvt_pk_bf16_f32 v94, v185, v186
	v_cvt_pk_bf16_f32 v95, v187, v194
	s_waitcnt lgkmcnt(6)
	s_nop 0
	v_mfma_f32_32x32x16_bf16 v[18:33], v[64:67], v[92:95], v[18:33]
	v_max3_f32 v51, v51, v123, v124
	v_max3_f32 v51, v51, v125, v126
	v_add_f32_e32 v50, v176, v177
	v_add_f32_e32 v50, v50, v178
	v_add_f32_e32 v50, v50, v179
	s_nop 0
	v_mfma_f32_32x32x16_bf16 v[2:17], v[60:63], v[92:95], v[2:17]
	v_cvt_pk_bf16_f32 v64, v195, v196
	v_cvt_pk_bf16_f32 v65, v197, v198
	v_cvt_pk_bf16_f32 v66, v146, v147
	v_cvt_pk_bf16_f32 v67, v148, v149
	v_max3_f32 v51, v51, v127, v128
	v_max3_f32 v51, v51, v129, v130
	v_add_f32_e32 v50, v50, v185
	v_add_f32_e32 v50, v50, v186
	v_add_f32_e32 v50, v50, v187
	v_add_f32_e32 v50, v50, v194
	s_waitcnt lgkmcnt(5)
	v_mfma_f32_32x32x16_bf16 v[18:33], v[68:71], v[64:67], v[18:33]
	v_max3_f32 v51, v51, v131, v132
	v_max3_f32 v51, v51, v133, v134
	v_add_f32_e32 v50, v50, v195
	v_add_f32_e32 v50, v50, v196
	v_add_f32_e32 v50, v50, v197
	v_add_f32_e32 v50, v50, v198
	s_waitcnt lgkmcnt(4)
	v_mfma_f32_32x32x16_bf16 v[2:17], v[72:75], v[64:67], v[2:17]
	v_cvt_pk_bf16_f32 v60, v150, v151
	v_cvt_pk_bf16_f32 v61, v152, v153
	v_cvt_pk_bf16_f32 v62, v199, v200
	v_cvt_pk_bf16_f32 v63, v201, v202
	v_max3_f32 v51, v51, v135, v136
	v_max3_f32 v51, v51, v137, v106
	v_add_f32_e32 v50, v50, v146
	v_add_f32_e32 v50, v50, v147
	v_add_f32_e32 v50, v50, v148
	v_add_f32_e32 v50, v50, v149
	s_waitcnt lgkmcnt(3)
	v_mfma_f32_32x32x16_bf16 v[18:33], v[76:79], v[60:63], v[18:33]
	v_max3_f32 v51, v51, v107, v108
	v_max3_f32 v51, v51, v109, v110
	v_add_f32_e32 v50, v50, v150
	v_add_f32_e32 v50, v50, v151
	v_add_f32_e32 v50, v50, v152
	v_add_f32_e32 v50, v50, v153
	s_waitcnt lgkmcnt(2)
	v_mfma_f32_32x32x16_bf16 v[2:17], v[80:83], v[60:63], v[2:17]
	v_cvt_pk_bf16_f32 v64, v203, v204
	v_cvt_pk_bf16_f32 v65, v205, v206
	v_cvt_pk_bf16_f32 v66, v207, v208
	v_cvt_pk_bf16_f32 v67, v209, v210
	v_max3_f32 v51, v51, v111, v112
	v_max3_f32 v51, v51, v113, v114
	v_add_f32_e32 v50, v50, v199
	v_add_f32_e32 v50, v50, v200
	v_add_f32_e32 v50, v50, v201
	v_add_f32_e32 v50, v50, v202
	s_waitcnt lgkmcnt(1)
	v_mfma_f32_32x32x16_bf16 v[18:33], v[84:87], v[64:67], v[18:33]
	v_max3_f32 v51, v51, v115, v116
	v_max3_f32 v51, v51, v117, v118
	v_add_f32_e32 v50, v50, v203
	v_add_f32_e32 v50, v50, v204
	v_add_f32_e32 v50, v50, v205
	v_add_f32_e32 v50, v50, v206
	s_waitcnt lgkmcnt(0)
	v_mfma_f32_32x32x16_bf16 v[2:17], v[88:91], v[64:67], v[2:17]
	v_max3_f32 v51, v51, v119, v120
	v_max3_f32 v51, v51, v121, v121
	v_add_f32_e32 v50, v50, v207
	v_add_f32_e32 v50, v50, v208
	v_add_f32_e32 v50, v50, v209
	v_add_f32_e32 v50, v50, v210
	s_setprio 0
	ds_read_b128 v[146:149], v165 offset:9248
	ds_read_b128 v[60:63], v165 offset:13856
	v_add_f32_e32 v50, v1, v50
	v_mov_b32_e32 v1, v51
	s_nop 1
	v_permlane32_swap_b32_e32 v51, v1
	v_max_f32_e32 v1, v1, v1
	v_max_f32_e32 v51, v51, v51
	v_max_f32_e32 v1, v51, v1
	v_cmp_lt_f32_e32 vcc, s52, v1
	s_cbranch_vccz .LBB0_643
	v_max_f32_e32 v1, v1, v1
	v_max_f32_e32 v68, 0, v1
	v_add_f32_e32 v183, v183, v68
	v_xor_b32_e32 v34, 0x80000000, v183
	v_pk_add_f32 v[122:123], v[122:123], v[68:69] op_sel_hi:[1,0] neg_lo:[0,1] neg_hi:[0,1]
	v_pk_add_f32 v[106:107], v[106:107], v[68:69] op_sel_hi:[1,0] neg_lo:[0,1] neg_hi:[0,1]
	v_pk_add_f32 v[124:125], v[124:125], v[68:69] op_sel_hi:[1,0] neg_lo:[0,1] neg_hi:[0,1]
	v_pk_add_f32 v[108:109], v[108:109], v[68:69] op_sel_hi:[1,0] neg_lo:[0,1] neg_hi:[0,1]
	v_pk_add_f32 v[126:127], v[126:127], v[68:69] op_sel_hi:[1,0] neg_lo:[0,1] neg_hi:[0,1]
	v_pk_add_f32 v[110:111], v[110:111], v[68:69] op_sel_hi:[1,0] neg_lo:[0,1] neg_hi:[0,1]
	v_pk_add_f32 v[128:129], v[128:129], v[68:69] op_sel_hi:[1,0] neg_lo:[0,1] neg_hi:[0,1]
	v_pk_add_f32 v[112:113], v[112:113], v[68:69] op_sel_hi:[1,0] neg_lo:[0,1] neg_hi:[0,1]
	v_pk_add_f32 v[130:131], v[130:131], v[68:69] op_sel_hi:[1,0] neg_lo:[0,1] neg_hi:[0,1]
	v_pk_add_f32 v[114:115], v[114:115], v[68:69] op_sel_hi:[1,0] neg_lo:[0,1] neg_hi:[0,1]
	v_pk_add_f32 v[132:133], v[132:133], v[68:69] op_sel_hi:[1,0] neg_lo:[0,1] neg_hi:[0,1]
	v_pk_add_f32 v[116:117], v[116:117], v[68:69] op_sel_hi:[1,0] neg_lo:[0,1] neg_hi:[0,1]
	v_pk_add_f32 v[134:135], v[134:135], v[68:69] op_sel_hi:[1,0] neg_lo:[0,1] neg_hi:[0,1]
	v_pk_add_f32 v[118:119], v[118:119], v[68:69] op_sel_hi:[1,0] neg_lo:[0,1] neg_hi:[0,1]
	v_pk_add_f32 v[136:137], v[136:137], v[68:69] op_sel_hi:[1,0] neg_lo:[0,1] neg_hi:[0,1]
	v_pk_add_f32 v[120:121], v[120:121], v[68:69] op_sel_hi:[1,0] neg_lo:[0,1] neg_hi:[0,1]
	v_exp_f32_e64 v68, -v68
	v_mov_b32_e32 v35, v34
	v_mov_b32_e32 v36, v34
	v_mov_b32_e32 v37, v34
	v_mov_b32_e32 v38, v34
	v_mov_b32_e32 v39, v34
	v_mov_b32_e32 v40, v34
	v_mov_b32_e32 v41, v34
	v_mov_b32_e32 v42, v34
	v_mov_b32_e32 v43, v34
	v_mov_b32_e32 v44, v34
	v_mov_b32_e32 v45, v34
	v_mov_b32_e32 v46, v34
	v_mov_b32_e32 v47, v34
	v_mov_b32_e32 v48, v34
	v_mov_b32_e32 v49, v34
	s_nop 11
	v_pk_mul_f32 v[32:33], v[32:33], v[68:69] op_sel_hi:[1,0]
	v_pk_mul_f32 v[30:31], v[30:31], v[68:69] op_sel_hi:[1,0]
	v_pk_mul_f32 v[28:29], v[28:29], v[68:69] op_sel_hi:[1,0]
	v_pk_mul_f32 v[26:27], v[26:27], v[68:69] op_sel_hi:[1,0]
	v_pk_mul_f32 v[24:25], v[24:25], v[68:69] op_sel_hi:[1,0]
	v_pk_mul_f32 v[22:23], v[22:23], v[68:69] op_sel_hi:[1,0]
	v_pk_mul_f32 v[20:21], v[20:21], v[68:69] op_sel_hi:[1,0]
	v_pk_mul_f32 v[18:19], v[18:19], v[68:69] op_sel_hi:[1,0]
	v_pk_mul_f32 v[16:17], v[16:17], v[68:69] op_sel_hi:[1,0]
	v_pk_mul_f32 v[14:15], v[14:15], v[68:69] op_sel_hi:[1,0]
	v_pk_mul_f32 v[12:13], v[12:13], v[68:69] op_sel_hi:[1,0]
	v_pk_mul_f32 v[10:11], v[10:11], v[68:69] op_sel_hi:[1,0]
	v_pk_mul_f32 v[8:9], v[8:9], v[68:69] op_sel_hi:[1,0]
	v_pk_mul_f32 v[6:7], v[6:7], v[68:69] op_sel_hi:[1,0]
	v_pk_mul_f32 v[4:5], v[4:5], v[68:69] op_sel_hi:[1,0]
	v_pk_mul_f32 v[2:3], v[2:3], v[68:69] op_sel_hi:[1,0]
	v_mul_f32_e32 v50, v50, v68

.LBB0_661:
	s_add_i32 s26, s13, -7
	s_lshl_b32 s92, s26, 13
	s_add_u32 vcc_lo, s100, s92
	s_addc_u32 vcc_hi, s101, 0
	global_load_dwordx4 v[2:5], v248, vcc
	s_add_i32 s26, s13, -8
	s_lshl_b32 s92, s26, 7
	s_add_u32 vcc_lo, s98, s92
	s_addc_u32 vcc_hi, s99, 0
	global_load_dwordx4 v[6:9], v249, vcc
	s_mul_i32 s28, s27, 0x2400
	s_add_i32 s26, s13, -7
	s_add_i32 s29, s28, 0xffffdc00
	s_cmp_lg_u32 s27, 0
	s_cselect_b32 s29, s29, 0x9000
	v_add_u32_e32 v1, s29, v195
	ds_read_b128 v[10:13], v1 offset:36864
	ds_read_b128 v[66:69], v1 offset:36896
	ds_read_b128 v[70:73], v1 offset:41472
	ds_read_b128 v[74:77], v1 offset:41504
	ds_read_b128 v[128:131], v1 offset:36928
	ds_read_b128 v[132:135], v1 offset:36960
	ds_read_b128 v[148:151], v1 offset:41536
	ds_read_b128 v[160:163], v1 offset:41568
	s_setprio 3
	v_cvt_pk_bf16_f32 v210, v116, v117
	v_cvt_pk_bf16_f32 v211, v118, v119
	v_cvt_pk_bf16_f32 v212, v112, v113
	v_cvt_pk_bf16_f32 v213, v114, v115
	s_waitcnt lgkmcnt(7)
	s_nop 0
	v_mfma_f32_32x32x16_bf16 v[16:31], v[10:13], v[210:213], v[16:31]
	v_add_f32_e32 v1, v116, v117
	v_add_f32_e32 v1, v1, v118
	v_add_f32_e32 v1, v1, v119
	s_waitcnt lgkmcnt(5)
	v_mfma_f32_32x32x16_bf16 v[32:47], v[70:73], v[210:213], v[32:47]
	v_cvt_pk_bf16_f32 v10, v187, v186
	v_cvt_pk_bf16_f32 v11, v185, v184
	v_cvt_pk_bf16_f32 v12, v147, v146
	v_cvt_pk_bf16_f32 v13, v145, v144
	v_add_f32_e32 v1, v1, v112
	v_add_f32_e32 v1, v1, v113
	v_add_f32_e32 v1, v1, v114
	v_add_f32_e32 v1, v1, v115
	s_nop 0
	v_mfma_f32_32x32x16_bf16 v[16:31], v[66:69], v[10:13], v[16:31]
	v_add_f32_e32 v1, v1, v187
	v_add_f32_e32 v1, v1, v186
	v_add_f32_e32 v1, v1, v185
	v_add_f32_e32 v1, v1, v184
	s_waitcnt lgkmcnt(4)
	v_mfma_f32_32x32x16_bf16 v[32:47], v[74:77], v[10:13], v[32:47]
	v_cvt_pk_bf16_f32 v66, v143, v142
	v_cvt_pk_bf16_f32 v67, v141, v140
	v_cvt_pk_bf16_f32 v68, v139, v138
	v_cvt_pk_bf16_f32 v69, v137, v136
	v_add_f32_e32 v1, v1, v147
	v_add_f32_e32 v1, v1, v146
	v_add_f32_e32 v1, v1, v145
	v_add_f32_e32 v1, v1, v144
	s_waitcnt lgkmcnt(3)
	v_mfma_f32_32x32x16_bf16 v[16:31], v[128:131], v[66:69], v[16:31]
	v_add_f32_e32 v1, v1, v143
	v_add_f32_e32 v1, v1, v142
	v_add_f32_e32 v1, v1, v141
	v_add_f32_e32 v1, v1, v140
	s_waitcnt lgkmcnt(1)
	v_mfma_f32_32x32x16_bf16 v[32:47], v[148:151], v[66:69], v[32:47]
	v_cvt_pk_bf16_f32 v10, v123, v122
	v_cvt_pk_bf16_f32 v11, v121, v120
	v_cvt_pk_bf16_f32 v12, v127, v126
	v_cvt_pk_bf16_f32 v13, v125, v124
	v_add_f32_e32 v1, v1, v139
	v_add_f32_e32 v1, v1, v138
	v_add_f32_e32 v1, v1, v137
	v_add_f32_e32 v1, v1, v136
	s_nop 0
	v_mfma_f32_32x32x16_bf16 v[16:31], v[132:135], v[10:13], v[16:31]
	v_add_f32_e32 v1, v1, v123
	v_add_f32_e32 v1, v1, v122
	v_add_f32_e32 v1, v1, v121
	v_add_f32_e32 v1, v1, v120
	s_waitcnt lgkmcnt(0)
	v_mfma_f32_32x32x16_bf16 v[32:47], v[160:163], v[10:13], v[32:47]
	v_add_f32_e32 v1, v1, v127
	v_add_f32_e32 v1, v1, v126
	v_add_f32_e32 v1, v1, v125
	v_add_f32_e32 v1, v1, v124
	s_setprio 2
	s_waitcnt lgkmcnt(0)
	s_barrier
	ds_read_b128 v[240:243], v195 offset:18432
	ds_read_b128 v[244:247], v195 offset:23040
	ds_read_b128 v[66:69], v195 offset:18464
	ds_read_b128 v[74:77], v195 offset:23072
	ds_read_b128 v[144:147], v195 offset:18496
	ds_read_b128 v[148:151], v195 offset:18528
	ds_read_b128 v[160:163], v195 offset:23104
	ds_read_b128 v[184:187], v195 offset:23136
	s_waitcnt lgkmcnt(6)
	v_mfma_f32_32x32x16_bf16 v[128:143], v[240:243], v[180:183], v[48:63]
	v_exp_f32_e32 v166, v96
	v_exp_f32_e32 v167, v97
	v_exp_f32_e32 v210, v98
	v_exp_f32_e32 v211, v99
	s_waitcnt lgkmcnt(5)
	v_mfma_f32_32x32x16_bf16 v[112:127], v[244:247], v[180:183], v[48:63]
	v_exp_f32_e32 v212, v100
	v_exp_f32_e32 v213, v101
	v_exp_f32_e32 v214, v102
	v_exp_f32_e32 v215, v103
	v_mfma_f32_32x32x16_bf16 v[128:143], v[66:69], v[176:179], v[128:143]
	v_exp_f32_e32 v100, v104
	v_exp_f32_e32 v101, v105
	v_exp_f32_e32 v102, v106
	v_exp_f32_e32 v103, v107
	s_waitcnt lgkmcnt(4)
	v_mfma_f32_32x32x16_bf16 v[112:127], v[74:77], v[176:179], v[112:127]
	v_exp_f32_e32 v104, v108
	v_exp_f32_e32 v105, v109
	v_exp_f32_e32 v106, v110
	v_exp_f32_e32 v107, v111
	s_waitcnt lgkmcnt(3)
	v_mfma_f32_32x32x16_bf16 v[128:143], v[144:147], v[172:175], v[128:143]
	v_exp_f32_e32 v108, v80
	v_exp_f32_e32 v109, v81
	v_exp_f32_e32 v110, v82
	v_exp_f32_e32 v111, v83
	s_waitcnt lgkmcnt(1)
	v_mfma_f32_32x32x16_bf16 v[112:127], v[160:163], v[172:175], v[112:127]
	v_exp_f32_e32 v144, v84
	v_exp_f32_e32 v145, v85
	v_exp_f32_e32 v146, v86
	v_exp_f32_e32 v147, v87
	v_mfma_f32_32x32x16_bf16 v[128:143], v[148:151], v[168:171], v[128:143]
	v_exp_f32_e32 v216, v88
	v_exp_f32_e32 v217, v89
	v_exp_f32_e32 v218, v90
	v_exp_f32_e32 v219, v91
	s_waitcnt lgkmcnt(0)
	v_mfma_f32_32x32x16_bf16 v[112:127], v[184:187], v[168:171], v[112:127]
	v_exp_f32_e32 v148, v92
	v_exp_f32_e32 v149, v93
	v_exp_f32_e32 v150, v94
	v_exp_f32_e32 v151, v95
	s_cmp_gt_i32 s27, 2
	s_cselect_b32 s29, -3, 2
	s_add_i32 s29, s29, s27
	v_add_u32_e32 v92, s28, v195
	s_add_i32 s28, s13, -6
	s_mulk_i32 s29, 0x2400
	s_min_u32 s28, s28, s12
	v_add_u32_e32 v10, s29, v208
	s_min_u32 s26, s26, s12
	s_lshl_b32 s92, s28, 13
	s_waitcnt vmcnt(3)
	ds_write_b128 v208, v[152:155]
	s_waitcnt vmcnt(2)
	ds_write_b128 v10, v[156:159] offset:36864
	s_add_u32 vcc_lo, s100, s92
	s_addc_u32 vcc_hi, s101, 0
	global_load_dwordx4 v[10:13], v248, vcc
	s_lshl_b32 s92, s26, 7
	v_add_f32_e32 v1, v64, v1
	s_add_u32 vcc_lo, s98, s92
	s_addc_u32 vcc_hi, s99, 0
	global_load_dwordx4 v[160:163], v249, vcc
	s_add_i32 s29, s27, 1
	ds_read_b128 v[240:243], v195 offset:27648
	ds_read_b128 v[244:247], v195 offset:32256
	ds_read_b128 v[64:67], v92 offset:41472
	ds_read_b128 v[68:71], v92 offset:36864
	ds_read_b128 v[72:75], v92 offset:36896
	ds_read_b128 v[76:79], v92 offset:41504
	ds_read_b128 v[80:83], v92 offset:36928
	ds_read_b128 v[84:87], v92 offset:41536
	ds_read_b128 v[88:91], v92 offset:36960
	ds_read_b128 v[92:95], v92 offset:41568
	s_setprio 1
	v_cvt_pk_bf16_f32 v96, v166, v167
	v_cvt_pk_bf16_f32 v97, v210, v211
	v_cvt_pk_bf16_f32 v98, v212, v213
	v_cvt_pk_bf16_f32 v99, v214, v215
	s_waitcnt lgkmcnt(6)
	s_nop 0
	v_mfma_f32_32x32x16_bf16 v[16:31], v[68:71], v[96:99], v[16:31]
	v_add_f32_e32 v184, v166, v167
	v_add_f32_e32 v184, v184, v210
	v_add_f32_e32 v184, v184, v211
	s_nop 0
	v_mfma_f32_32x32x16_bf16 v[32:47], v[64:67], v[96:99], v[32:47]
	v_cvt_pk_bf16_f32 v68, v100, v101
	v_cvt_pk_bf16_f32 v69, v102, v103
	v_cvt_pk_bf16_f32 v70, v104, v105
	v_cvt_pk_bf16_f32 v71, v106, v107
	v_add_f32_e32 v184, v184, v212
	v_add_f32_e32 v184, v184, v213
	v_add_f32_e32 v184, v184, v214
	v_add_f32_e32 v184, v184, v215
	s_waitcnt lgkmcnt(5)
	v_mfma_f32_32x32x16_bf16 v[16:31], v[72:75], v[68:71], v[16:31]
	v_add_f32_e32 v184, v184, v100
	v_add_f32_e32 v184, v184, v101
	v_add_f32_e32 v184, v184, v102
	v_add_f32_e32 v184, v184, v103
	s_waitcnt lgkmcnt(4)
	v_mfma_f32_32x32x16_bf16 v[32:47], v[76:79], v[68:71], v[32:47]
	v_cvt_pk_bf16_f32 v64, v108, v109
	v_cvt_pk_bf16_f32 v65, v110, v111
	v_cvt_pk_bf16_f32 v66, v144, v145
	v_cvt_pk_bf16_f32 v67, v146, v147
	v_add_f32_e32 v184, v184, v104
	v_add_f32_e32 v184, v184, v105
	v_add_f32_e32 v184, v184, v106
	v_add_f32_e32 v184, v184, v107
	s_waitcnt lgkmcnt(3)
	v_mfma_f32_32x32x16_bf16 v[16:31], v[80:83], v[64:67], v[16:31]
	v_add_f32_e32 v184, v184, v108
	v_add_f32_e32 v184, v184, v109
	v_add_f32_e32 v184, v184, v110
	v_add_f32_e32 v184, v184, v111
	s_waitcnt lgkmcnt(2)
	v_mfma_f32_32x32x16_bf16 v[32:47], v[84:87], v[64:67], v[32:47]
	v_cvt_pk_bf16_f32 v68, v216, v217
	v_cvt_pk_bf16_f32 v69, v218, v219
	v_cvt_pk_bf16_f32 v70, v148, v149
	v_cvt_pk_bf16_f32 v71, v150, v151
	v_add_f32_e32 v184, v184, v144
	v_add_f32_e32 v184, v184, v145
	v_add_f32_e32 v184, v184, v146
	v_add_f32_e32 v184, v184, v147
	s_waitcnt lgkmcnt(1)
	v_mfma_f32_32x32x16_bf16 v[16:31], v[88:91], v[68:71], v[16:31]
	v_add_f32_e32 v184, v184, v216
	v_add_f32_e32 v184, v184, v217
	v_add_f32_e32 v184, v184, v218
	v_add_f32_e32 v184, v184, v219
	s_waitcnt lgkmcnt(0)
	v_mfma_f32_32x32x16_bf16 v[32:47], v[92:95], v[68:71], v[32:47]
	v_add_f32_e32 v184, v184, v148
	v_add_f32_e32 v184, v184, v149
	v_add_f32_e32 v184, v184, v150
	v_add_f32_e32 v184, v184, v151
	s_setprio 0
	ds_read_b128 v[68:71], v195 offset:27680
	ds_read_b128 v[76:79], v195 offset:32288
	ds_read_b128 v[80:83], v195 offset:27712
	ds_read_b128 v[84:87], v195 offset:27744
	ds_read_b128 v[88:91], v195 offset:32320
	ds_read_b128 v[92:95], v195 offset:32352
	s_cmp_lg_u32 s27, 4
	s_cselect_b32 s26, s29, 0
	s_waitcnt lgkmcnt(6)
	v_mfma_f32_32x32x16_bf16 v[144:159], v[240:243], v[180:183], v[48:63]
	v_exp_f32_e32 v166, v128
	v_exp_f32_e32 v167, v129
	v_exp_f32_e32 v185, v130
	v_exp_f32_e32 v186, v131
	s_waitcnt lgkmcnt(5)
	v_mfma_f32_32x32x16_bf16 v[96:111], v[244:247], v[180:183], v[48:63]
	v_exp_f32_e32 v128, v132
	v_exp_f32_e32 v129, v133
	v_exp_f32_e32 v130, v134
	v_exp_f32_e32 v131, v135
	v_mfma_f32_32x32x16_bf16 v[144:159], v[68:71], v[176:179], v[144:159]
	v_exp_f32_e32 v132, v136
	v_exp_f32_e32 v133, v137
	v_exp_f32_e32 v134, v138
	v_exp_f32_e32 v135, v139
	s_waitcnt lgkmcnt(4)
	v_mfma_f32_32x32x16_bf16 v[96:111], v[76:79], v[176:179], v[96:111]
	v_exp_f32_e32 v136, v140
	v_exp_f32_e32 v137, v141
	v_exp_f32_e32 v138, v142
	v_exp_f32_e32 v139, v143
	s_waitcnt lgkmcnt(3)
	v_mfma_f32_32x32x16_bf16 v[144:159], v[80:83], v[172:175], v[144:159]
	v_exp_f32_e32 v140, v112
	v_exp_f32_e32 v141, v113
	v_exp_f32_e32 v142, v114
	v_exp_f32_e32 v143, v115
	s_waitcnt lgkmcnt(1)
	v_mfma_f32_32x32x16_bf16 v[96:111], v[88:91], v[172:175], v[96:111]
	v_exp_f32_e32 v187, v116
	v_exp_f32_e32 v210, v117
	v_exp_f32_e32 v211, v118
	v_exp_f32_e32 v212, v119
	v_mfma_f32_32x32x16_bf16 v[144:159], v[84:87], v[168:171], v[144:159]
	v_exp_f32_e32 v116, v120
	v_exp_f32_e32 v117, v121
	v_exp_f32_e32 v118, v122
	v_exp_f32_e32 v119, v123
	s_waitcnt lgkmcnt(0)
	v_mfma_f32_32x32x16_bf16 v[96:111], v[92:95], v[168:171], v[96:111]
	v_exp_f32_e32 v120, v124
	v_exp_f32_e32 v121, v125
	v_exp_f32_e32 v122, v126
	v_exp_f32_e32 v123, v127
	s_cmp_gt_i32 s26, 2
	s_cselect_b32 s27, -3, 2
	s_add_i32 s27, s27, s26
	s_mulk_i32 s27, 0x2400
	s_waitcnt vmcnt(3)
	ds_write_b128 v208, v[2:5] offset:9216
	v_add_u32_e32 v2, s27, v208
	s_add_i32 s27, s26, 1
	s_cmp_lg_u32 s26, 4
	s_cselect_b32 s26, s27, 0
	s_add_i32 s27, s13, -5
	s_min_u32 s27, s27, s12
	s_lshl_b32 s92, s27, 13
	s_waitcnt vmcnt(2)
	ds_write_b128 v2, v[6:9] offset:36864
	s_add_u32 vcc_lo, s100, s92
	s_addc_u32 vcc_hi, s101, 0
	global_load_dwordx4 v[6:9], v248, vcc
	s_lshl_b32 s92, s28, 7
	s_add_u32 vcc_lo, s98, s92
	s_addc_u32 vcc_hi, s99, 0
	global_load_dwordx4 v[2:5], v249, vcc
	s_nop 0
	s_mul_i32 s28, s26, 0x2400
	s_add_i32 s29, s28, 0xffffdc00
	s_cmp_lg_u32 s26, 0
	s_cselect_b32 s29, s29, 0x9000
	v_add_u32_e32 v92, s29, v195
	ds_read_b128 v[64:67], v92 offset:36864
	ds_read_b128 v[68:71], v92 offset:36896
	ds_read_b128 v[72:75], v92 offset:41472
	ds_read_b128 v[76:79], v92 offset:41504
	ds_read_b128 v[80:83], v92 offset:36928
	ds_read_b128 v[84:87], v92 offset:36960
	ds_read_b128 v[88:91], v92 offset:41536
	ds_read_b128 v[92:95], v92 offset:41568
	s_setprio 3
	v_cvt_pk_bf16_f32 v112, v166, v167
	v_cvt_pk_bf16_f32 v113, v185, v186
	v_cvt_pk_bf16_f32 v114, v128, v129
	v_cvt_pk_bf16_f32 v115, v130, v131
	s_waitcnt lgkmcnt(7)
	s_nop 0
	v_mfma_f32_32x32x16_bf16 v[16:31], v[64:67], v[112:115], v[16:31]
	v_add_f32_e32 v213, v166, v167
	v_add_f32_e32 v213, v213, v185
	v_add_f32_e32 v213, v213, v186
	s_waitcnt lgkmcnt(5)
	v_mfma_f32_32x32x16_bf16 v[32:47], v[72:75], v[112:115], v[32:47]
	v_cvt_pk_bf16_f32 v64, v132, v133
	v_cvt_pk_bf16_f32 v65, v134, v135
	v_cvt_pk_bf16_f32 v66, v136, v137
	v_cvt_pk_bf16_f32 v67, v138, v139
	v_add_f32_e32 v213, v213, v128
	v_add_f32_e32 v213, v213, v129
	v_add_f32_e32 v213, v213, v130
	v_add_f32_e32 v213, v213, v131
	s_nop 0
	v_mfma_f32_32x32x16_bf16 v[16:31], v[68:71], v[64:67], v[16:31]
	v_add_f32_e32 v213, v213, v132
	v_add_f32_e32 v213, v213, v133
	v_add_f32_e32 v213, v213, v134
	v_add_f32_e32 v213, v213, v135
	s_waitcnt lgkmcnt(4)
	v_mfma_f32_32x32x16_bf16 v[32:47], v[76:79], v[64:67], v[32:47]
	v_cvt_pk_bf16_f32 v68, v140, v141
	v_cvt_pk_bf16_f32 v69, v142, v143
	v_cvt_pk_bf16_f32 v70, v187, v210
	v_cvt_pk_bf16_f32 v71, v211, v212
	v_add_f32_e32 v213, v213, v136
	v_add_f32_e32 v213, v213, v137
	v_add_f32_e32 v213, v213, v138
	v_add_f32_e32 v213, v213, v139
	s_waitcnt lgkmcnt(3)
	v_mfma_f32_32x32x16_bf16 v[16:31], v[80:83], v[68:71], v[16:31]
	v_add_f32_e32 v213, v213, v140
	v_add_f32_e32 v213, v213, v141
	v_add_f32_e32 v213, v213, v142
	v_add_f32_e32 v213, v213, v143
	s_waitcnt lgkmcnt(1)
	v_mfma_f32_32x32x16_bf16 v[32:47], v[88:91], v[68:71], v[32:47]
	v_cvt_pk_bf16_f32 v64, v116, v117
	v_cvt_pk_bf16_f32 v65, v118, v119
	v_cvt_pk_bf16_f32 v66, v120, v121
	v_cvt_pk_bf16_f32 v67, v122, v123
	v_add_f32_e32 v213, v213, v187
	v_add_f32_e32 v213, v213, v210
	v_add_f32_e32 v213, v213, v211
	v_add_f32_e32 v213, v213, v212
	s_nop 0
	v_mfma_f32_32x32x16_bf16 v[16:31], v[84:87], v[64:67], v[16:31]
	v_add_f32_e32 v213, v213, v116
	v_add_f32_e32 v213, v213, v117
	v_add_f32_e32 v213, v213, v118
	v_add_f32_e32 v213, v213, v119
	s_waitcnt lgkmcnt(0)
	v_mfma_f32_32x32x16_bf16 v[32:47], v[92:95], v[64:67], v[32:47]
	v_add_f32_e32 v213, v213, v120
	v_add_f32_e32 v213, v213, v121
	v_add_f32_e32 v213, v213, v122
	v_add_f32_e32 v213, v213, v123
	s_setprio 2
	s_waitcnt lgkmcnt(0)
	s_barrier
	ds_read_b128 v[240:243], v195
	ds_read_b128 v[244:247], v195 offset:4608
	ds_read_b128 v[116:119], v195 offset:32
	ds_read_b128 v[120:123], v195 offset:4640
	ds_read_b128 v[124:127], v195 offset:64
	ds_read_b128 v[128:131], v195 offset:4672
	ds_read_b128 v[132:135], v195 offset:96
	ds_read_b128 v[136:139], v195 offset:4704
	v_add_f32_e32 v1, v1, v184
	s_waitcnt lgkmcnt(6)
	v_mfma_f32_32x32x16_bf16 v[80:95], v[240:243], v[180:183], v[48:63]
	v_exp_f32_e32 v140, v144
	v_exp_f32_e32 v141, v145
	v_exp_f32_e32 v142, v146
	v_exp_f32_e32 v143, v147
	v_mfma_f32_32x32x16_bf16 v[64:79], v[244:247], v[180:183], v[48:63]
	v_exp_f32_e32 v144, v148
	v_exp_f32_e32 v145, v149
	v_exp_f32_e32 v146, v150
	v_exp_f32_e32 v147, v151
	s_waitcnt lgkmcnt(5)
	v_mfma_f32_32x32x16_bf16 v[80:95], v[116:119], v[176:179], v[80:95]
	v_exp_f32_e32 v148, v152
	v_exp_f32_e32 v149, v153
	v_exp_f32_e32 v150, v154
	v_exp_f32_e32 v151, v155
	s_waitcnt lgkmcnt(4)
	v_mfma_f32_32x32x16_bf16 v[64:79], v[120:123], v[176:179], v[64:79]
	v_exp_f32_e32 v152, v156
	v_exp_f32_e32 v153, v157
	v_exp_f32_e32 v154, v158
	v_exp_f32_e32 v155, v159
	s_waitcnt lgkmcnt(3)
	v_mfma_f32_32x32x16_bf16 v[80:95], v[124:127], v[172:175], v[80:95]
	v_exp_f32_e32 v156, v96
	v_exp_f32_e32 v157, v97
	v_exp_f32_e32 v158, v98
	v_exp_f32_e32 v159, v99
	s_waitcnt lgkmcnt(2)
	v_mfma_f32_32x32x16_bf16 v[64:79], v[128:131], v[172:175], v[64:79]
	v_exp_f32_e32 v166, v100
	v_exp_f32_e32 v167, v101
	v_exp_f32_e32 v184, v102
	v_exp_f32_e32 v185, v103
	s_waitcnt lgkmcnt(1)
	v_mfma_f32_32x32x16_bf16 v[80:95], v[132:135], v[168:171], v[80:95]
	v_exp_f32_e32 v186, v104
	v_exp_f32_e32 v187, v105
	v_exp_f32_e32 v210, v106
	v_exp_f32_e32 v211, v107
	s_waitcnt lgkmcnt(0)
	v_mfma_f32_32x32x16_bf16 v[64:79], v[136:139], v[168:171], v[64:79]
	v_exp_f32_e32 v212, v108
	v_exp_f32_e32 v214, v109
	v_exp_f32_e32 v215, v110
	v_exp_f32_e32 v216, v111
	s_cmp_gt_i32 s26, 2
	s_cselect_b32 s29, -3, 2
	s_add_i32 s29, s29, s26
	s_mulk_i32 s29, 0x2400
	s_waitcnt vmcnt(3)
	ds_write_b128 v208, v[10:13] offset:18432
	v_add_u32_e32 v10, s29, v208
	s_mov_b32 s29, 0x1da90000
	s_waitcnt vmcnt(2)
	ds_write_b128 v10, v[160:163] offset:36864
	s_add_i32 s92, s13, -4
	s_lshl_b32 s92, s92, 13
	s_add_u32 vcc_lo, s100, s92
	s_addc_u32 vcc_hi, s101, 0
	global_load_dwordx4 v[128:131], v248, vcc
	s_lshl_b32 s92, s27, 7
	s_add_u32 vcc_lo, s98, s92
	s_addc_u32 vcc_hi, s99, 0
	global_load_dwordx4 v[10:13], v249, vcc
	v_add_u32_e32 v124, s28, v195
	ds_read_b128 v[240:243], v195 offset:9216
	ds_read_b128 v[244:247], v195 offset:13824
	ds_read_b128 v[96:99], v124 offset:41472
	ds_read_b128 v[100:103], v124 offset:36864
	ds_read_b128 v[104:107], v124 offset:36896
	ds_read_b128 v[108:111], v124 offset:41504
	ds_read_b128 v[112:115], v124 offset:36928
	ds_read_b128 v[116:119], v124 offset:41536
	ds_read_b128 v[120:123], v124 offset:36960
	ds_read_b128 v[124:127], v124 offset:41568
	v_add_f32_e32 v1, v1, v213
	s_add_i32 s28, s26, 1
	s_setprio 1
	v_cvt_pk_bf16_f32 v132, v140, v141
	v_cvt_pk_bf16_f32 v133, v142, v143
	v_cvt_pk_bf16_f32 v134, v144, v145
	v_cvt_pk_bf16_f32 v135, v146, v147
	s_waitcnt lgkmcnt(6)
	s_nop 0
	v_mfma_f32_32x32x16_bf16 v[16:31], v[100:103], v[132:135], v[16:31]
	v_add_f32_e32 v160, v140, v141
	v_add_f32_e32 v160, v160, v142
	v_add_f32_e32 v160, v160, v143
	s_nop 0
	v_mfma_f32_32x32x16_bf16 v[32:47], v[96:99], v[132:135], v[32:47]
	v_cvt_pk_bf16_f32 v100, v148, v149
	v_cvt_pk_bf16_f32 v101, v150, v151
	v_cvt_pk_bf16_f32 v102, v152, v153
	v_cvt_pk_bf16_f32 v103, v154, v155
	v_add_f32_e32 v160, v160, v144
	v_add_f32_e32 v160, v160, v145
	v_add_f32_e32 v160, v160, v146
	v_add_f32_e32 v160, v160, v147
	s_waitcnt lgkmcnt(5)
	v_mfma_f32_32x32x16_bf16 v[16:31], v[104:107], v[100:103], v[16:31]
	v_add_f32_e32 v160, v160, v148
	v_add_f32_e32 v160, v160, v149
	v_add_f32_e32 v160, v160, v150
	v_add_f32_e32 v160, v160, v151
	s_waitcnt lgkmcnt(4)
	v_mfma_f32_32x32x16_bf16 v[32:47], v[108:111], v[100:103], v[32:47]
	v_cvt_pk_bf16_f32 v96, v156, v157
	v_cvt_pk_bf16_f32 v97, v158, v159
	v_cvt_pk_bf16_f32 v98, v166, v167
	v_cvt_pk_bf16_f32 v99, v184, v185
	v_add_f32_e32 v160, v160, v152
	v_add_f32_e32 v160, v160, v153
	v_add_f32_e32 v160, v160, v154
	v_add_f32_e32 v160, v160, v155
	s_waitcnt lgkmcnt(3)
	v_mfma_f32_32x32x16_bf16 v[16:31], v[112:115], v[96:99], v[16:31]
	v_add_f32_e32 v160, v160, v156
	v_add_f32_e32 v160, v160, v157
	v_add_f32_e32 v160, v160, v158
	v_add_f32_e32 v160, v160, v159
	s_waitcnt lgkmcnt(2)
	v_mfma_f32_32x32x16_bf16 v[32:47], v[116:119], v[96:99], v[32:47]
	v_cvt_pk_bf16_f32 v100, v186, v187
	v_cvt_pk_bf16_f32 v101, v210, v211
	v_cvt_pk_bf16_f32 v102, v212, v214
	v_cvt_pk_bf16_f32 v103, v215, v216
	v_add_f32_e32 v160, v160, v166
	v_add_f32_e32 v160, v160, v167
	v_add_f32_e32 v160, v160, v184
	v_add_f32_e32 v160, v160, v185
	s_waitcnt lgkmcnt(1)
	v_mfma_f32_32x32x16_bf16 v[16:31], v[120:123], v[100:103], v[16:31]
	v_add_f32_e32 v160, v160, v186
	v_add_f32_e32 v160, v160, v187
	v_add_f32_e32 v160, v160, v210
	v_add_f32_e32 v160, v160, v211
	s_waitcnt lgkmcnt(0)
	v_mfma_f32_32x32x16_bf16 v[32:47], v[124:127], v[100:103], v[32:47]
	v_add_f32_e32 v160, v160, v212
	v_add_f32_e32 v160, v160, v214
	v_add_f32_e32 v160, v160, v215
	v_add_f32_e32 v160, v160, v216
	s_setprio 0
	ds_read_b128 v[132:135], v195 offset:9248
	ds_read_b128 v[140:143], v195 offset:13856
	ds_read_b128 v[144:147], v195 offset:9280
	ds_read_b128 v[148:151], v195 offset:9312
	ds_read_b128 v[152:155], v195 offset:13888
	ds_read_b128 v[156:159], v195 offset:13920
	s_cmp_lg_u32 s26, 4
	s_cselect_b32 s26, s28, 0
	s_waitcnt lgkmcnt(6)
	v_mfma_f32_32x32x16_bf16 v[112:127], v[240:243], v[180:183], v[48:63]
	v_exp_f32_e32 v161, v80
	v_exp_f32_e32 v162, v81
	v_exp_f32_e32 v163, v82
	v_exp_f32_e32 v164, v83
	s_waitcnt lgkmcnt(5)
	v_mfma_f32_32x32x16_bf16 v[96:111], v[244:247], v[180:183], v[48:63]
	v_exp_f32_e32 v165, v84
	v_exp_f32_e32 v166, v85
	v_exp_f32_e32 v167, v86
	v_exp_f32_e32 v184, v87
	v_mfma_f32_32x32x16_bf16 v[112:127], v[132:135], v[176:179], v[112:127]
	v_exp_f32_e32 v136, v88
	v_exp_f32_e32 v137, v89
	v_exp_f32_e32 v138, v90
	v_exp_f32_e32 v139, v91
	s_waitcnt lgkmcnt(4)
	v_mfma_f32_32x32x16_bf16 v[96:111], v[140:143], v[176:179], v[96:111]
	v_exp_f32_e32 v185, v92
	v_exp_f32_e32 v186, v93
	v_exp_f32_e32 v187, v94
	v_exp_f32_e32 v210, v95
	s_waitcnt lgkmcnt(3)
	v_mfma_f32_32x32x16_bf16 v[112:127], v[144:147], v[172:175], v[112:127]
	v_exp_f32_e32 v140, v64
	v_exp_f32_e32 v141, v65
	v_exp_f32_e32 v142, v66
	v_exp_f32_e32 v143, v67
	s_waitcnt lgkmcnt(1)
	v_mfma_f32_32x32x16_bf16 v[96:111], v[152:155], v[172:175], v[96:111]
	v_exp_f32_e32 v144, v68
	v_exp_f32_e32 v145, v69
	v_exp_f32_e32 v146, v70
	v_exp_f32_e32 v147, v71
	v_mfma_f32_32x32x16_bf16 v[112:127], v[148:151], v[168:171], v[112:127]
	v_exp_f32_e32 v152, v72
	v_exp_f32_e32 v153, v73
	v_exp_f32_e32 v154, v74
	v_exp_f32_e32 v155, v75
	s_waitcnt lgkmcnt(0)
	v_mfma_f32_32x32x16_bf16 v[96:111], v[156:159], v[168:171], v[96:111]
	v_exp_f32_e32 v148, v76
	v_exp_f32_e32 v149, v77
	v_exp_f32_e32 v150, v78
	v_exp_f32_e32 v151, v79
	s_cmp_gt_i32 s26, 2
	s_cselect_b32 s27, -3, 2
	s_add_i32 s27, s27, s26
	s_mulk_i32 s27, 0x2400
	s_waitcnt vmcnt(3)
	ds_write_b128 v208, v[6:9] offset:27648
	v_add_u32_e32 v6, s27, v208
	s_add_i32 s27, s26, 1
	s_cmp_lg_u32 s26, 4
	s_cselect_b32 s27, s27, 0
	s_add_i32 s26, s13, -3
	s_min_u32 s28, s26, s12
	s_lshl_b32 s92, s28, 13
	s_waitcnt vmcnt(2)
	ds_write_b128 v6, v[2:5] offset:36864
	s_add_u32 vcc_lo, s100, s92
	s_addc_u32 vcc_hi, s101, 0
	global_load_dwordx4 v[6:9], v248, vcc
	s_nop 0
	s_add_i32 s92, s13, -4
	s_lshl_b32 s92, s92, 7
	s_add_u32 vcc_lo, s98, s92
	s_addc_u32 vcc_hi, s99, 0
	global_load_dwordx4 v[2:5], v249, vcc
	s_mul_i32 s29, s27, 0x2400
	s_add_i32 s34, s29, 0xffffdc00
	s_cmp_lg_u32 s27, 0
	s_cselect_b32 s34, s34, 0x9000
	v_add_u32_e32 v14, s34, v195
	ds_read_b128 v[64:67], v14 offset:36864
	ds_read_b128 v[68:71], v14 offset:36896
	ds_read_b128 v[72:75], v14 offset:41472
	ds_read_b128 v[76:79], v14 offset:41504
	ds_read_b128 v[80:83], v14 offset:36928
	ds_read_b128 v[84:87], v14 offset:36960
	ds_read_b128 v[88:91], v14 offset:41536
	ds_read_b128 v[92:95], v14 offset:41568
	s_setprio 3
	v_cvt_pk_bf16_f32 v132, v161, v162
	v_cvt_pk_bf16_f32 v133, v163, v164
	v_cvt_pk_bf16_f32 v134, v165, v166
	v_cvt_pk_bf16_f32 v135, v167, v184
	s_waitcnt lgkmcnt(7)
	s_nop 0
	v_mfma_f32_32x32x16_bf16 v[16:31], v[64:67], v[132:135], v[16:31]
	v_add_f32_e32 v14, v161, v162
	v_add_f32_e32 v14, v14, v163
	v_add_f32_e32 v14, v14, v164
	s_waitcnt lgkmcnt(5)
	v_mfma_f32_32x32x16_bf16 v[32:47], v[72:75], v[132:135], v[32:47]
	v_cvt_pk_bf16_f32 v64, v136, v137
	v_cvt_pk_bf16_f32 v65, v138, v139
	v_cvt_pk_bf16_f32 v66, v185, v186
	v_cvt_pk_bf16_f32 v67, v187, v210
	v_add_f32_e32 v14, v14, v165
	v_add_f32_e32 v14, v14, v166
	v_add_f32_e32 v14, v14, v167
	v_add_f32_e32 v14, v14, v184
	s_nop 0
	v_mfma_f32_32x32x16_bf16 v[16:31], v[68:71], v[64:67], v[16:31]
	v_add_f32_e32 v14, v14, v136
	v_add_f32_e32 v14, v14, v137
	v_add_f32_e32 v14, v14, v138
	v_add_f32_e32 v14, v14, v139
	s_waitcnt lgkmcnt(4)
	v_mfma_f32_32x32x16_bf16 v[32:47], v[76:79], v[64:67], v[32:47]
	v_cvt_pk_bf16_f32 v68, v140, v141
	v_cvt_pk_bf16_f32 v69, v142, v143
	v_cvt_pk_bf16_f32 v70, v144, v145
	v_cvt_pk_bf16_f32 v71, v146, v147
	v_add_f32_e32 v14, v14, v185
	v_add_f32_e32 v14, v14, v186
	v_add_f32_e32 v14, v14, v187
	v_add_f32_e32 v14, v14, v210
	s_waitcnt lgkmcnt(3)
	v_mfma_f32_32x32x16_bf16 v[16:31], v[80:83], v[68:71], v[16:31]
	v_add_f32_e32 v14, v14, v140
	v_add_f32_e32 v14, v14, v141
	v_add_f32_e32 v14, v14, v142
	v_add_f32_e32 v14, v14, v143
	s_waitcnt lgkmcnt(1)
	v_mfma_f32_32x32x16_bf16 v[32:47], v[88:91], v[68:71], v[32:47]
	v_cvt_pk_bf16_f32 v64, v152, v153
	v_cvt_pk_bf16_f32 v65, v154, v155
	v_cvt_pk_bf16_f32 v66, v148, v149
	v_cvt_pk_bf16_f32 v67, v150, v151
	v_add_f32_e32 v14, v14, v144
	v_add_f32_e32 v14, v14, v145
	v_add_f32_e32 v14, v14, v146
	v_add_f32_e32 v14, v14, v147
	s_nop 0
	v_mfma_f32_32x32x16_bf16 v[16:31], v[84:87], v[64:67], v[16:31]
	v_add_f32_e32 v14, v14, v152
	v_add_f32_e32 v14, v14, v153
	v_add_f32_e32 v14, v14, v154
	v_add_f32_e32 v14, v14, v155
	s_waitcnt lgkmcnt(0)
	v_mfma_f32_32x32x16_bf16 v[32:47], v[92:95], v[64:67], v[32:47]
	v_add_f32_e32 v14, v14, v148
	v_add_f32_e32 v14, v14, v149
	v_add_f32_e32 v14, v14, v150
	v_add_f32_e32 v14, v14, v151
	s_setprio 2
	s_waitcnt lgkmcnt(0)
	s_barrier
	ds_read_b128 v[240:243], v195 offset:18432
	ds_read_b128 v[244:247], v195 offset:23040
	ds_read_b128 v[136:139], v195 offset:18464
	ds_read_b128 v[140:143], v195 offset:23072
	ds_read_b128 v[144:147], v195 offset:18496
	ds_read_b128 v[148:151], v195 offset:23104
	ds_read_b128 v[152:155], v195 offset:18528
	ds_read_b128 v[156:159], v195 offset:23136
	v_add_f32_e32 v1, v1, v160
	s_waitcnt lgkmcnt(6)
	v_mfma_f32_32x32x16_bf16 v[80:95], v[240:243], v[180:183], v[48:63]
	v_exp_f32_e32 v160, v112
	v_exp_f32_e32 v161, v113
	v_exp_f32_e32 v162, v114
	v_exp_f32_e32 v163, v115
	v_mfma_f32_32x32x16_bf16 v[64:79], v[244:247], v[180:183], v[48:63]
	v_exp_f32_e32 v164, v116
	v_exp_f32_e32 v165, v117
	v_exp_f32_e32 v166, v118
	v_exp_f32_e32 v167, v119
	s_waitcnt lgkmcnt(5)
	v_mfma_f32_32x32x16_bf16 v[80:95], v[136:139], v[176:179], v[80:95]
	v_exp_f32_e32 v184, v120
	v_exp_f32_e32 v185, v121
	v_exp_f32_e32 v186, v122
	v_exp_f32_e32 v187, v123
	s_waitcnt lgkmcnt(4)
	v_mfma_f32_32x32x16_bf16 v[64:79], v[140:143], v[176:179], v[64:79]
	v_exp_f32_e32 v136, v124
	v_exp_f32_e32 v137, v125
	v_exp_f32_e32 v138, v126
	v_exp_f32_e32 v139, v127
	s_waitcnt lgkmcnt(3)
	v_mfma_f32_32x32x16_bf16 v[80:95], v[144:147], v[172:175], v[80:95]
	v_exp_f32_e32 v140, v96
	v_exp_f32_e32 v141, v97
	v_exp_f32_e32 v142, v98
	v_exp_f32_e32 v143, v99
	s_waitcnt lgkmcnt(2)
	v_mfma_f32_32x32x16_bf16 v[64:79], v[148:151], v[172:175], v[64:79]
	v_exp_f32_e32 v144, v100
	v_exp_f32_e32 v145, v101
	v_exp_f32_e32 v146, v102
	v_exp_f32_e32 v147, v103
	s_waitcnt lgkmcnt(1)
	v_mfma_f32_32x32x16_bf16 v[80:95], v[152:155], v[168:171], v[80:95]
	v_exp_f32_e32 v148, v104
	v_exp_f32_e32 v149, v105
	v_exp_f32_e32 v150, v106
	v_exp_f32_e32 v151, v107
	s_waitcnt lgkmcnt(0)
	v_mfma_f32_32x32x16_bf16 v[64:79], v[156:159], v[168:171], v[64:79]
	v_exp_f32_e32 v152, v108
	v_exp_f32_e32 v153, v109
	v_exp_f32_e32 v154, v110
	v_exp_f32_e32 v155, v111
	s_cmp_gt_i32 s27, 2
	s_cselect_b32 s34, -3, 2
	s_waitcnt vmcnt(3)
	ds_write_b128 v208, v[128:131]
	s_add_i32 s34, s34, s27
	v_add_u32_e32 v128, s29, v195
	s_add_i32 s29, s13, -2
	s_mulk_i32 s34, 0x2400
	s_min_u32 s29, s29, s12
	v_add_u32_e32 v15, s34, v208
	s_lshl_b32 s92, s29, 13
	s_waitcnt vmcnt(2)
	ds_write_b128 v15, v[10:13] offset:36864
	s_add_u32 vcc_lo, s100, s92
	s_addc_u32 vcc_hi, s101, 0
	global_load_dwordx4 v[10:13], v248, vcc
	s_lshl_b32 s92, s28, 7
	v_add_f32_e32 v1, v1, v14
	s_add_u32 vcc_lo, s98, s92
	s_addc_u32 vcc_hi, s99, 0
	global_load_dwordx4 v[112:115], v249, vcc
	ds_read_b128 v[240:243], v195 offset:27648
	ds_read_b128 v[244:247], v195 offset:32256
	ds_read_b128 v[96:99], v128 offset:41472
	ds_read_b128 v[100:103], v128 offset:36864
	ds_read_b128 v[104:107], v128 offset:36896
	ds_read_b128 v[108:111], v128 offset:41504
	ds_read_b128 v[116:119], v128 offset:36928
	ds_read_b128 v[120:123], v128 offset:41536
	ds_read_b128 v[124:127], v128 offset:36960
	ds_read_b128 v[128:131], v128 offset:41568
	s_add_i32 s34, s27, 1
	s_setprio 1
	v_cvt_pk_bf16_f32 v132, v160, v161
	v_cvt_pk_bf16_f32 v133, v162, v163
	v_cvt_pk_bf16_f32 v134, v164, v165
	v_cvt_pk_bf16_f32 v135, v166, v167
	s_waitcnt lgkmcnt(6)
	s_nop 0
	v_mfma_f32_32x32x16_bf16 v[16:31], v[100:103], v[132:135], v[16:31]
	v_add_f32_e32 v14, v160, v161
	v_add_f32_e32 v14, v14, v162
	v_add_f32_e32 v14, v14, v163
	s_nop 0
	v_mfma_f32_32x32x16_bf16 v[32:47], v[96:99], v[132:135], v[32:47]
	v_cvt_pk_bf16_f32 v100, v184, v185
	v_cvt_pk_bf16_f32 v101, v186, v187
	v_cvt_pk_bf16_f32 v102, v136, v137
	v_cvt_pk_bf16_f32 v103, v138, v139
	v_add_f32_e32 v14, v14, v164
	v_add_f32_e32 v14, v14, v165
	v_add_f32_e32 v14, v14, v166
	v_add_f32_e32 v14, v14, v167
	s_waitcnt lgkmcnt(5)
	v_mfma_f32_32x32x16_bf16 v[16:31], v[104:107], v[100:103], v[16:31]
	v_add_f32_e32 v14, v14, v184
	v_add_f32_e32 v14, v14, v185
	v_add_f32_e32 v14, v14, v186
	v_add_f32_e32 v14, v14, v187
	s_waitcnt lgkmcnt(4)
	v_mfma_f32_32x32x16_bf16 v[32:47], v[108:111], v[100:103], v[32:47]
	v_cvt_pk_bf16_f32 v96, v140, v141
	v_cvt_pk_bf16_f32 v97, v142, v143
	v_cvt_pk_bf16_f32 v98, v144, v145
	v_cvt_pk_bf16_f32 v99, v146, v147
	v_add_f32_e32 v14, v14, v136
	v_add_f32_e32 v14, v14, v137
	v_add_f32_e32 v14, v14, v138
	v_add_f32_e32 v14, v14, v139
	s_waitcnt lgkmcnt(3)
	v_mfma_f32_32x32x16_bf16 v[16:31], v[116:119], v[96:99], v[16:31]
	v_add_f32_e32 v14, v14, v140
	v_add_f32_e32 v14, v14, v141
	v_add_f32_e32 v14, v14, v142
	v_add_f32_e32 v14, v14, v143
	s_waitcnt lgkmcnt(2)
	v_mfma_f32_32x32x16_bf16 v[32:47], v[120:123], v[96:99], v[32:47]
	v_cvt_pk_bf16_f32 v100, v148, v149
	v_cvt_pk_bf16_f32 v101, v150, v151
	v_cvt_pk_bf16_f32 v102, v152, v153
	v_cvt_pk_bf16_f32 v103, v154, v155
	v_add_f32_e32 v14, v14, v144
	v_add_f32_e32 v14, v14, v145
	v_add_f32_e32 v14, v14, v146
	v_add_f32_e32 v14, v14, v147
	s_waitcnt lgkmcnt(1)
	v_mfma_f32_32x32x16_bf16 v[16:31], v[124:127], v[100:103], v[16:31]
	v_add_f32_e32 v14, v14, v148
	v_add_f32_e32 v14, v14, v149
	v_add_f32_e32 v14, v14, v150
	v_add_f32_e32 v14, v14, v151
	s_waitcnt lgkmcnt(0)
	v_mfma_f32_32x32x16_bf16 v[32:47], v[128:131], v[100:103], v[32:47]
	v_add_f32_e32 v14, v14, v152
	v_add_f32_e32 v14, v14, v153
	v_add_f32_e32 v14, v14, v154
	v_add_f32_e32 v14, v14, v155
	s_setprio 0
	ds_read_b128 v[116:119], v195 offset:27680
	ds_read_b128 v[124:127], v195 offset:32288
	ds_read_b128 v[128:131], v195 offset:27712
	ds_read_b128 v[132:135], v195 offset:27744
	ds_read_b128 v[136:139], v195 offset:32320
	ds_read_b128 v[140:143], v195 offset:32352
	s_cmp_lg_u32 s27, 4
	s_cselect_b32 s27, s34, 0
	s_waitcnt lgkmcnt(6)
	v_mfma_f32_32x32x16_bf16 v[152:167], v[240:243], v[180:183], v[48:63]
	v_exp_f32_e32 v15, v80
	v_exp_f32_e32 v144, v81
	v_exp_f32_e32 v145, v82
	v_exp_f32_e32 v146, v83
	s_waitcnt lgkmcnt(5)
	v_mfma_f32_32x32x16_bf16 v[96:111], v[244:247], v[180:183], v[48:63]
	v_exp_f32_e32 v147, v84
	v_exp_f32_e32 v148, v85
	v_exp_f32_e32 v149, v86
	v_exp_f32_e32 v150, v87
	v_mfma_f32_32x32x16_bf16 v[152:167], v[116:119], v[176:179], v[152:167]
	v_exp_f32_e32 v120, v88
	v_exp_f32_e32 v121, v89
	v_exp_f32_e32 v122, v90
	v_exp_f32_e32 v123, v91
	s_waitcnt lgkmcnt(4)
	v_mfma_f32_32x32x16_bf16 v[96:111], v[124:127], v[176:179], v[96:111]
	v_exp_f32_e32 v151, v92
	v_exp_f32_e32 v184, v93
	v_exp_f32_e32 v185, v94
	v_exp_f32_e32 v186, v95
	s_waitcnt lgkmcnt(3)
	v_mfma_f32_32x32x16_bf16 v[152:167], v[128:131], v[172:175], v[152:167]
	v_exp_f32_e32 v124, v64
	v_exp_f32_e32 v125, v65
	v_exp_f32_e32 v126, v66
	v_exp_f32_e32 v127, v67
	s_waitcnt lgkmcnt(1)
	v_mfma_f32_32x32x16_bf16 v[96:111], v[136:139], v[172:175], v[96:111]
	v_exp_f32_e32 v128, v68
	v_exp_f32_e32 v129, v69
	v_exp_f32_e32 v130, v70
	v_exp_f32_e32 v131, v71
	v_mfma_f32_32x32x16_bf16 v[152:167], v[132:135], v[168:171], v[152:167]
	v_exp_f32_e32 v136, v72
	v_exp_f32_e32 v137, v73
	v_exp_f32_e32 v138, v74
	v_exp_f32_e32 v139, v75
	s_waitcnt lgkmcnt(0)
	v_mfma_f32_32x32x16_bf16 v[96:111], v[140:143], v[168:171], v[96:111]
	v_exp_f32_e32 v132, v76
	v_exp_f32_e32 v133, v77
	v_exp_f32_e32 v134, v78
	v_exp_f32_e32 v135, v79
	s_cmp_gt_i32 s27, 2
	s_cselect_b32 s28, -3, 2
	s_add_i32 s28, s28, s27
	s_mulk_i32 s28, 0x2400
	s_waitcnt vmcnt(3)
	ds_write_b128 v208, v[6:9] offset:9216
	v_add_u32_e32 v6, s28, v208
	s_add_i32 s28, s27, 1
	s_cmp_lg_u32 s27, 4
	s_cselect_b32 s27, s28, 0
	s_add_i32 s28, s13, -1
	s_min_u32 s28, s28, s12
	s_lshl_b32 s92, s28, 13
	s_waitcnt vmcnt(2)
	ds_write_b128 v6, v[2:5] offset:36864
	s_add_u32 vcc_lo, s100, s92
	s_addc_u32 vcc_hi, s101, 0
	global_load_dwordx4 v[6:9], v248, vcc
	s_lshl_b32 s92, s29, 7
	s_add_u32 vcc_lo, s98, s92
	s_addc_u32 vcc_hi, s99, 0
	global_load_dwordx4 v[2:5], v249, vcc
	s_nop 0
	s_mul_i32 s29, s27, 0x2400
	s_add_i32 s34, s29, 0xffffdc00
	s_cmp_lg_u32 s27, 0
	s_cselect_b32 s34, s34, 0x9000
	v_add_u32_e32 v92, s34, v195
	ds_read_b128 v[64:67], v92 offset:36864
	ds_read_b128 v[68:71], v92 offset:36896
	ds_read_b128 v[72:75], v92 offset:41472
	ds_read_b128 v[76:79], v92 offset:41504
	ds_read_b128 v[80:83], v92 offset:36928
	ds_read_b128 v[84:87], v92 offset:36960
	ds_read_b128 v[88:91], v92 offset:41536
	ds_read_b128 v[92:95], v92 offset:41568
	s_setprio 3
	v_cvt_pk_bf16_f32 v116, v15, v144
	v_cvt_pk_bf16_f32 v117, v145, v146
	v_cvt_pk_bf16_f32 v118, v147, v148
	v_cvt_pk_bf16_f32 v119, v149, v150
	s_waitcnt lgkmcnt(7)
	s_nop 0
	v_mfma_f32_32x32x16_bf16 v[16:31], v[64:67], v[116:119], v[16:31]
	v_add_f32_e32 v187, v15, v144
	v_add_f32_e32 v187, v187, v145
	v_add_f32_e32 v187, v187, v146
	s_waitcnt lgkmcnt(5)
	v_mfma_f32_32x32x16_bf16 v[32:47], v[72:75], v[116:119], v[32:47]
	v_cvt_pk_bf16_f32 v64, v120, v121
	v_cvt_pk_bf16_f32 v65, v122, v123
	v_cvt_pk_bf16_f32 v66, v151, v184
	v_cvt_pk_bf16_f32 v67, v185, v186
	v_add_f32_e32 v187, v187, v147
	v_add_f32_e32 v187, v187, v148
	v_add_f32_e32 v187, v187, v149
	v_add_f32_e32 v187, v187, v150
	s_nop 0
	v_mfma_f32_32x32x16_bf16 v[16:31], v[68:71], v[64:67], v[16:31]
	v_add_f32_e32 v187, v187, v120
	v_add_f32_e32 v187, v187, v121
	v_add_f32_e32 v187, v187, v122
	v_add_f32_e32 v187, v187, v123
	s_waitcnt lgkmcnt(4)
	v_mfma_f32_32x32x16_bf16 v[32:47], v[76:79], v[64:67], v[32:47]
	v_cvt_pk_bf16_f32 v68, v124, v125
	v_cvt_pk_bf16_f32 v69, v126, v127
	v_cvt_pk_bf16_f32 v70, v128, v129
	v_cvt_pk_bf16_f32 v71, v130, v131
	v_add_f32_e32 v187, v187, v151
	v_add_f32_e32 v187, v187, v184
	v_add_f32_e32 v187, v187, v185
	v_add_f32_e32 v187, v187, v186
	s_waitcnt lgkmcnt(3)
	v_mfma_f32_32x32x16_bf16 v[16:31], v[80:83], v[68:71], v[16:31]
	v_add_f32_e32 v187, v187, v124
	v_add_f32_e32 v187, v187, v125
	v_add_f32_e32 v187, v187, v126
	v_add_f32_e32 v187, v187, v127
	s_waitcnt lgkmcnt(1)
	v_mfma_f32_32x32x16_bf16 v[32:47], v[88:91], v[68:71], v[32:47]
	v_cvt_pk_bf16_f32 v64, v136, v137
	v_cvt_pk_bf16_f32 v65, v138, v139
	v_cvt_pk_bf16_f32 v66, v132, v133
	v_cvt_pk_bf16_f32 v67, v134, v135
	v_add_f32_e32 v187, v187, v128
	v_add_f32_e32 v187, v187, v129
	v_add_f32_e32 v187, v187, v130
	v_add_f32_e32 v187, v187, v131
	s_nop 0
	v_mfma_f32_32x32x16_bf16 v[16:31], v[84:87], v[64:67], v[16:31]
	v_add_f32_e32 v187, v187, v136
	v_add_f32_e32 v187, v187, v137
	v_add_f32_e32 v187, v187, v138
	v_add_f32_e32 v187, v187, v139
	s_waitcnt lgkmcnt(0)
	v_mfma_f32_32x32x16_bf16 v[32:47], v[92:95], v[64:67], v[32:47]
	v_add_f32_e32 v187, v187, v132
	v_add_f32_e32 v187, v187, v133
	v_add_f32_e32 v187, v187, v134
	v_add_f32_e32 v187, v187, v135
	s_setprio 2
	s_waitcnt lgkmcnt(0)
	s_barrier
	ds_read_b128 v[240:243], v195
	ds_read_b128 v[244:247], v195 offset:4608
	ds_read_b128 v[72:75], v195 offset:32
	ds_read_b128 v[76:79], v195 offset:4640
	ds_read_b128 v[80:83], v195 offset:64
	ds_read_b128 v[84:87], v195 offset:4672
	ds_read_b128 v[88:91], v195 offset:96
	ds_read_b128 v[92:95], v195 offset:4704
	v_add_f32_e32 v1, v1, v14
	s_waitcnt lgkmcnt(6)
	v_mfma_f32_32x32x16_bf16 v[136:151], v[240:243], v[180:183], v[48:63]
	v_exp_f32_e32 v14, v152
	v_exp_f32_e32 v15, v153
	v_exp_f32_e32 v116, v154
	v_exp_f32_e32 v117, v155
	v_mfma_f32_32x32x16_bf16 v[120:135], v[244:247], v[180:183], v[48:63]
	v_exp_f32_e32 v118, v156
	v_exp_f32_e32 v119, v157
	v_exp_f32_e32 v184, v158
	v_exp_f32_e32 v185, v159
	s_waitcnt lgkmcnt(5)
	v_mfma_f32_32x32x16_bf16 v[136:151], v[72:75], v[176:179], v[136:151]
	v_exp_f32_e32 v186, v160
	v_exp_f32_e32 v210, v161
	v_exp_f32_e32 v211, v162
	v_exp_f32_e32 v212, v163
	s_waitcnt lgkmcnt(4)
	v_mfma_f32_32x32x16_bf16 v[120:135], v[76:79], v[176:179], v[120:135]
	v_exp_f32_e32 v160, v164
	v_exp_f32_e32 v161, v165
	v_exp_f32_e32 v162, v166
	v_exp_f32_e32 v163, v167
	s_waitcnt lgkmcnt(3)
	v_mfma_f32_32x32x16_bf16 v[136:151], v[80:83], v[172:175], v[136:151]
	v_exp_f32_e32 v164, v96
	v_exp_f32_e32 v165, v97
	v_exp_f32_e32 v166, v98
	v_exp_f32_e32 v167, v99
	s_waitcnt lgkmcnt(2)
	v_mfma_f32_32x32x16_bf16 v[120:135], v[84:87], v[172:175], v[120:135]
	v_exp_f32_e32 v96, v100
	v_exp_f32_e32 v97, v101
	v_exp_f32_e32 v98, v102
	v_exp_f32_e32 v99, v103
	s_waitcnt lgkmcnt(1)
	v_mfma_f32_32x32x16_bf16 v[136:151], v[88:91], v[168:171], v[136:151]
	v_exp_f32_e32 v100, v104
	v_exp_f32_e32 v101, v105
	v_exp_f32_e32 v102, v106
	v_exp_f32_e32 v103, v107
	s_waitcnt lgkmcnt(0)
	v_mfma_f32_32x32x16_bf16 v[120:135], v[92:95], v[168:171], v[120:135]
	v_exp_f32_e32 v104, v108
	v_exp_f32_e32 v105, v109
	v_exp_f32_e32 v106, v110
	v_exp_f32_e32 v107, v111
	s_cmp_gt_i32 s27, 2
	s_cselect_b32 s34, -3, 2
	s_add_i32 s34, s34, s27
	s_mulk_i32 s34, 0x2400
	v_add_u32_e32 v88, s29, v195
	s_min_u32 s29, s13, s12
	s_waitcnt vmcnt(3)
	ds_write_b128 v208, v[10:13] offset:18432
	v_add_u32_e32 v10, s34, v208
	s_lshl_b32 s92, s29, 13
	s_waitcnt vmcnt(2)
	ds_write_b128 v10, v[112:115] offset:36864
	s_add_u32 vcc_lo, s100, s92
	s_addc_u32 vcc_hi, s101, 0
	global_load_dwordx4 v[152:155], v248, vcc
	s_lshl_b32 s92, s28, 7
	s_add_u32 vcc_lo, s98, s92
	s_addc_u32 vcc_hi, s99, 0
	global_load_dwordx4 v[156:159], v249, vcc
	ds_read_b128 v[240:243], v195 offset:9216
	ds_read_b128 v[244:247], v195 offset:13824
	ds_read_b128 v[10:13], v88 offset:41472
	ds_read_b128 v[64:67], v88 offset:36864
	ds_read_b128 v[68:71], v88 offset:36896
	ds_read_b128 v[72:75], v88 offset:41504
	ds_read_b128 v[76:79], v88 offset:36928
	ds_read_b128 v[80:83], v88 offset:41536
	ds_read_b128 v[84:87], v88 offset:36960
	ds_read_b128 v[88:91], v88 offset:41568
	v_add_f32_e32 v1, v1, v187
	s_setprio 1
	v_mov_b32_e32 v109, v136
	v_cvt_pk_bf16_f32 v92, v14, v15
	v_cvt_pk_bf16_f32 v93, v116, v117
	v_cvt_pk_bf16_f32 v94, v118, v119
	v_cvt_pk_bf16_f32 v95, v184, v185
	s_waitcnt lgkmcnt(6)
	s_nop 0
	v_mfma_f32_32x32x16_bf16 v[16:31], v[64:67], v[92:95], v[16:31]
	v_max3_f32 v109, v109, v137, v138
	v_max3_f32 v109, v109, v139, v140
	v_add_f32_e32 v108, v14, v15
	v_add_f32_e32 v108, v108, v116
	v_add_f32_e32 v108, v108, v117
	s_nop 0
	v_mfma_f32_32x32x16_bf16 v[32:47], v[10:13], v[92:95], v[32:47]
	v_cvt_pk_bf16_f32 v64, v186, v210
	v_cvt_pk_bf16_f32 v65, v211, v212
	v_cvt_pk_bf16_f32 v66, v160, v161
	v_cvt_pk_bf16_f32 v67, v162, v163
	v_max3_f32 v109, v109, v141, v142
	v_max3_f32 v109, v109, v143, v144
	v_add_f32_e32 v108, v108, v118
	v_add_f32_e32 v108, v108, v119
	v_add_f32_e32 v108, v108, v184
	v_add_f32_e32 v108, v108, v185
	s_waitcnt lgkmcnt(5)
	v_mfma_f32_32x32x16_bf16 v[16:31], v[68:71], v[64:67], v[16:31]
	v_max3_f32 v109, v109, v145, v146
	v_max3_f32 v109, v109, v147, v148
	v_add_f32_e32 v108, v108, v186
	v_add_f32_e32 v108, v108, v210
	v_add_f32_e32 v108, v108, v211
	v_add_f32_e32 v108, v108, v212
	s_waitcnt lgkmcnt(4)
	v_mfma_f32_32x32x16_bf16 v[32:47], v[72:75], v[64:67], v[32:47]
	v_cvt_pk_bf16_f32 v10, v164, v165
	v_cvt_pk_bf16_f32 v11, v166, v167
	v_cvt_pk_bf16_f32 v12, v96, v97
	v_cvt_pk_bf16_f32 v13, v98, v99
	v_max3_f32 v109, v109, v149, v150
	v_max3_f32 v109, v109, v151, v120
	v_add_f32_e32 v108, v108, v160
	v_add_f32_e32 v108, v108, v161
	v_add_f32_e32 v108, v108, v162
	v_add_f32_e32 v108, v108, v163
	s_waitcnt lgkmcnt(3)
	v_mfma_f32_32x32x16_bf16 v[16:31], v[76:79], v[10:13], v[16:31]
	v_max3_f32 v109, v109, v121, v122
	v_max3_f32 v109, v109, v123, v124
	v_add_f32_e32 v108, v108, v164
	v_add_f32_e32 v108, v108, v165
	v_add_f32_e32 v108, v108, v166
	v_add_f32_e32 v108, v108, v167
	s_waitcnt lgkmcnt(2)
	v_mfma_f32_32x32x16_bf16 v[32:47], v[80:83], v[10:13], v[32:47]
	v_cvt_pk_bf16_f32 v64, v100, v101
	v_cvt_pk_bf16_f32 v65, v102, v103
	v_cvt_pk_bf16_f32 v66, v104, v105
	v_cvt_pk_bf16_f32 v67, v106, v107
	v_max3_f32 v109, v109, v125, v126
	v_max3_f32 v109, v109, v127, v128
	v_add_f32_e32 v108, v108, v96
	v_add_f32_e32 v108, v108, v97
	v_add_f32_e32 v108, v108, v98
	v_add_f32_e32 v108, v108, v99
	s_waitcnt lgkmcnt(1)
	v_mfma_f32_32x32x16_bf16 v[16:31], v[84:87], v[64:67], v[16:31]
	v_max3_f32 v109, v109, v129, v130
	v_max3_f32 v109, v109, v131, v132
	v_add_f32_e32 v108, v108, v100
	v_add_f32_e32 v108, v108, v101
	v_add_f32_e32 v108, v108, v102
	v_add_f32_e32 v108, v108, v103
	s_waitcnt lgkmcnt(0)
	v_mfma_f32_32x32x16_bf16 v[32:47], v[88:91], v[64:67], v[32:47]
	v_max3_f32 v109, v109, v133, v134
	v_max3_f32 v109, v109, v135, v135
	v_add_f32_e32 v108, v108, v104
	v_add_f32_e32 v108, v108, v105
	v_add_f32_e32 v108, v108, v106
	v_add_f32_e32 v108, v108, v107
	s_setprio 0
	ds_read_b128 v[164:167], v195 offset:9248
	ds_read_b128 v[160:163], v195 offset:13856
	ds_read_b128 v[74:77], v195 offset:9280
	ds_read_b128 v[66:69], v195 offset:9312
	ds_read_b128 v[70:73], v195 offset:13888
	ds_read_b128 v[10:13], v195 offset:13920
	v_add_f32_e32 v64, v1, v108
	v_mov_b32_e32 v1, v109
	s_nop 1
	v_permlane32_swap_b32_e32 v109, v1
	v_max_f32_e32 v1, v1, v1
	v_max_f32_e32 v14, v109, v109
	v_max_f32_e32 v1, v14, v1
	v_cmp_lt_f32_e32 vcc, s52, v1
	s_cbranch_vccz .LBB0_663
	v_max_f32_e32 v1, v1, v1
	v_max_f32_e32 v14, 0, v1
	v_add_f32_e32 v209, v209, v14
	v_xor_b32_e32 v48, 0x80000000, v209
	v_pk_add_f32 v[136:137], v[136:137], v[14:15] op_sel_hi:[1,0] neg_lo:[0,1] neg_hi:[0,1]
	v_pk_add_f32 v[120:121], v[120:121], v[14:15] op_sel_hi:[1,0] neg_lo:[0,1] neg_hi:[0,1]
	v_pk_add_f32 v[138:139], v[138:139], v[14:15] op_sel_hi:[1,0] neg_lo:[0,1] neg_hi:[0,1]
	v_pk_add_f32 v[122:123], v[122:123], v[14:15] op_sel_hi:[1,0] neg_lo:[0,1] neg_hi:[0,1]
	v_pk_add_f32 v[140:141], v[140:141], v[14:15] op_sel_hi:[1,0] neg_lo:[0,1] neg_hi:[0,1]
	v_pk_add_f32 v[124:125], v[124:125], v[14:15] op_sel_hi:[1,0] neg_lo:[0,1] neg_hi:[0,1]
	v_pk_add_f32 v[142:143], v[142:143], v[14:15] op_sel_hi:[1,0] neg_lo:[0,1] neg_hi:[0,1]
	v_pk_add_f32 v[126:127], v[126:127], v[14:15] op_sel_hi:[1,0] neg_lo:[0,1] neg_hi:[0,1]
	v_pk_add_f32 v[144:145], v[144:145], v[14:15] op_sel_hi:[1,0] neg_lo:[0,1] neg_hi:[0,1]
	v_pk_add_f32 v[128:129], v[128:129], v[14:15] op_sel_hi:[1,0] neg_lo:[0,1] neg_hi:[0,1]
	v_pk_add_f32 v[146:147], v[146:147], v[14:15] op_sel_hi:[1,0] neg_lo:[0,1] neg_hi:[0,1]
	v_pk_add_f32 v[130:131], v[130:131], v[14:15] op_sel_hi:[1,0] neg_lo:[0,1] neg_hi:[0,1]
	v_pk_add_f32 v[148:149], v[148:149], v[14:15] op_sel_hi:[1,0] neg_lo:[0,1] neg_hi:[0,1]
	v_pk_add_f32 v[132:133], v[132:133], v[14:15] op_sel_hi:[1,0] neg_lo:[0,1] neg_hi:[0,1]
	v_pk_add_f32 v[150:151], v[150:151], v[14:15] op_sel_hi:[1,0] neg_lo:[0,1] neg_hi:[0,1]
	v_pk_add_f32 v[134:135], v[134:135], v[14:15] op_sel_hi:[1,0] neg_lo:[0,1] neg_hi:[0,1]
	v_exp_f32_e64 v14, -v14
	v_mov_b32_e32 v49, v48
	v_mov_b32_e32 v50, v48
	v_mov_b32_e32 v51, v48
	v_mov_b32_e32 v52, v48
	v_mov_b32_e32 v53, v48
	v_mov_b32_e32 v54, v48
	v_mov_b32_e32 v55, v48
	v_mov_b32_e32 v56, v48
	v_mov_b32_e32 v57, v48
	v_mov_b32_e32 v58, v48
	v_mov_b32_e32 v59, v48
	v_mov_b32_e32 v60, v48
	v_mov_b32_e32 v61, v48
	v_mov_b32_e32 v62, v48
	v_mov_b32_e32 v63, v48
	s_nop 11
	v_pk_mul_f32 v[30:31], v[30:31], v[14:15] op_sel_hi:[1,0]
	v_pk_mul_f32 v[28:29], v[28:29], v[14:15] op_sel_hi:[1,0]
	v_pk_mul_f32 v[26:27], v[26:27], v[14:15] op_sel_hi:[1,0]
	v_pk_mul_f32 v[24:25], v[24:25], v[14:15] op_sel_hi:[1,0]
	v_pk_mul_f32 v[22:23], v[22:23], v[14:15] op_sel_hi:[1,0]
	v_pk_mul_f32 v[20:21], v[20:21], v[14:15] op_sel_hi:[1,0]
	v_pk_mul_f32 v[18:19], v[18:19], v[14:15] op_sel_hi:[1,0]
	v_pk_mul_f32 v[16:17], v[16:17], v[14:15] op_sel_hi:[1,0]
	v_pk_mul_f32 v[46:47], v[46:47], v[14:15] op_sel_hi:[1,0]
	v_pk_mul_f32 v[44:45], v[44:45], v[14:15] op_sel_hi:[1,0]
	v_pk_mul_f32 v[42:43], v[42:43], v[14:15] op_sel_hi:[1,0]
	v_pk_mul_f32 v[40:41], v[40:41], v[14:15] op_sel_hi:[1,0]
	v_pk_mul_f32 v[38:39], v[38:39], v[14:15] op_sel_hi:[1,0]
	v_pk_mul_f32 v[36:37], v[36:37], v[14:15] op_sel_hi:[1,0]
	v_pk_mul_f32 v[34:35], v[34:35], v[14:15] op_sel_hi:[1,0]
	v_pk_mul_f32 v[32:33], v[32:33], v[14:15] op_sel_hi:[1,0]
	v_mul_f32_e32 v64, v64, v14
